# q_b tile epilogue: sum-of-squares loads of blocks 2..7 issued with block 1's (immediate offsets, spare registers) and both rope-table load pairs of a block issued together
# baseline (speedup 1.0000x reference)
.LBB0_400:
	s_waitcnt lgkmcnt(0)
	s_barrier
	ds_read_b128 v[224:227], v184
	ds_read_b128 v[228:231], v184 offset:1024
	ds_read_b128 v[232:235], v184 offset:2048
	ds_read_b128 v[236:239], v184 offset:3072
	ds_read_b128 v[190:193], v185
	ds_read_b128 v[194:197], v185 offset:1024
	ds_read_b128 v[198:201], v185 offset:2048
	ds_read_b128 v[204:207], v185 offset:3072
	ds_read_b128 v[208:211], v185 offset:4096
	ds_read_b128 v[212:215], v185 offset:5120
	ds_read_b128 v[216:219], v185 offset:6144
	ds_read_b128 v[220:223], v185 offset:7168
	s_movk_i32 vcc_lo, 0x6000
	s_cmp_eq_u32 m0, 2
	s_cselect_b32 vcc_lo, 0xffff4000, vcc_lo
	s_add_u32 m0, m0, 1
	s_cmp_eq_u32 m0, 3
	s_cselect_b32 m0, 0, m0
	v_add_u32_e32 v185, vcc_lo, v185
	v_add_u32_e32 v184, vcc_lo, v184
	v_xor_b32_e32 v185, 64, v185
	v_xor_b32_e32 v184, 64, v184
	s_waitcnt lgkmcnt(7)
	v_mfma_f32_16x16x32_bf16 v[172:175], v[224:227], v[190:193], v[172:175]
	v_mfma_f32_16x16x32_bf16 v[164:167], v[228:231], v[190:193], v[164:167]
	v_mfma_f32_16x16x32_bf16 v[156:159], v[232:235], v[190:193], v[156:159]
	v_mfma_f32_16x16x32_bf16 v[144:147], v[236:239], v[190:193], v[144:147]
	ds_read_b128 v[190:193], v185
	s_waitcnt lgkmcnt(7)
	v_mfma_f32_16x16x32_bf16 v[140:143], v[224:227], v[194:197], v[140:143]
	v_mfma_f32_16x16x32_bf16 v[128:131], v[228:231], v[194:197], v[128:131]
	v_mfma_f32_16x16x32_bf16 v[124:127], v[232:235], v[194:197], v[124:127]
	v_mfma_f32_16x16x32_bf16 v[116:119], v[236:239], v[194:197], v[116:119]
	ds_read_b128 v[194:197], v185 offset:1024
	s_waitcnt lgkmcnt(7)
	v_mfma_f32_16x16x32_bf16 v[104:107], v[224:227], v[198:201], v[104:107]
	v_mfma_f32_16x16x32_bf16 v[100:103], v[228:231], v[198:201], v[100:103]
	v_mfma_f32_16x16x32_bf16 v[92:95], v[232:235], v[198:201], v[92:95]
	v_mfma_f32_16x16x32_bf16 v[84:87], v[236:239], v[198:201], v[84:87]
	ds_read_b128 v[198:201], v185 offset:2048
	s_waitcnt lgkmcnt(7)
	v_mfma_f32_16x16x32_bf16 v[80:83], v[224:227], v[204:207], v[80:83]
	v_mfma_f32_16x16x32_bf16 v[76:79], v[228:231], v[204:207], v[76:79]
	v_mfma_f32_16x16x32_bf16 v[64:67], v[232:235], v[204:207], v[64:67]
	v_mfma_f32_16x16x32_bf16 v[60:63], v[236:239], v[204:207], v[60:63]
	ds_read_b128 v[204:207], v185 offset:3072
	s_waitcnt lgkmcnt(7)
	v_mfma_f32_16x16x32_bf16 v[56:59], v[224:227], v[208:211], v[56:59]
	v_mfma_f32_16x16x32_bf16 v[52:55], v[228:231], v[208:211], v[52:55]
	v_mfma_f32_16x16x32_bf16 v[48:51], v[232:235], v[208:211], v[48:51]
	v_mfma_f32_16x16x32_bf16 v[44:47], v[236:239], v[208:211], v[44:47]
	ds_read_b128 v[208:211], v185 offset:4096
	s_waitcnt lgkmcnt(7)
	v_mfma_f32_16x16x32_bf16 v[40:43], v[224:227], v[212:215], v[40:43]
	v_mfma_f32_16x16x32_bf16 v[36:39], v[228:231], v[212:215], v[36:39]
	v_mfma_f32_16x16x32_bf16 v[32:35], v[232:235], v[212:215], v[32:35]
	v_mfma_f32_16x16x32_bf16 v[28:31], v[236:239], v[212:215], v[28:31]
	ds_read_b128 v[212:215], v185 offset:5120
	s_waitcnt lgkmcnt(7)
	v_mfma_f32_16x16x32_bf16 v[24:27], v[224:227], v[216:219], v[24:27]
	v_mfma_f32_16x16x32_bf16 v[20:23], v[228:231], v[216:219], v[20:23]
	v_mfma_f32_16x16x32_bf16 v[16:19], v[232:235], v[216:219], v[16:19]
	v_mfma_f32_16x16x32_bf16 v[12:15], v[236:239], v[216:219], v[12:15]
	ds_read_b128 v[216:219], v185 offset:6144
	s_waitcnt lgkmcnt(7)
	v_mfma_f32_16x16x32_bf16 v[8:11], v[224:227], v[220:223], v[8:11]
	v_mfma_f32_16x16x32_bf16 v[4:7], v[228:231], v[220:223], v[4:7]
	v_mfma_f32_16x16x32_bf16 v[0:3], v[232:235], v[220:223], v[0:3]
	v_mfma_f32_16x16x32_bf16 v[112:115], v[236:239], v[220:223], v[112:115]
	ds_read_b128 v[220:223], v185 offset:7168
	ds_read_b128 v[224:227], v184
	ds_read_b128 v[228:231], v184 offset:1024
	ds_read_b128 v[232:235], v184 offset:2048
	ds_read_b128 v[236:239], v184 offset:3072
	s_movk_i32 vcc_lo, 0x6000
	s_cmp_eq_u32 m0, 2
	s_cselect_b32 vcc_lo, 0xffff4000, vcc_lo
	s_add_u32 m0, m0, 1
	s_cmp_eq_u32 m0, 3
	s_cselect_b32 m0, 0, m0
	v_add_u32_e32 v185, vcc_lo, v185
	v_add_u32_e32 v184, vcc_lo, v184
	v_xor_b32_e32 v185, 64, v185
	v_xor_b32_e32 v184, 64, v184
	s_sub_u32 vcc_lo, s0, s98
	v_add_u32_e32 v186, vcc_lo, v178
	v_add_u32_e32 v187, vcc_lo, v180
	s_barrier
	s_waitcnt lgkmcnt(0)
	v_mfma_f32_16x16x32_bf16 v[172:175], v[224:227], v[190:193], v[172:175]
	s_waitcnt vmcnt(11)
	v_mfma_f32_16x16x32_bf16 v[164:167], v[228:231], v[190:193], v[164:167]
	ds_write_b128 v183, v[168:171]
	v_add_u32_e32 v168, 0xa700000, v186
	v_mfma_f32_16x16x32_bf16 v[156:159], v[232:235], v[190:193], v[156:159]
	global_load_dwordx4 v[168:171], v168, s[98:99] offset:128
	v_mfma_f32_16x16x32_bf16 v[144:147], v[236:239], v[190:193], v[144:147]
	s_waitcnt vmcnt(11)
	ds_write_b128 v183, v[160:163] offset:2048
	v_mfma_f32_16x16x32_bf16 v[140:143], v[224:227], v[194:197], v[140:143]
	v_add_u32_e32 v160, 0xa706000, v186
	v_mfma_f32_16x16x32_bf16 v[128:131], v[228:231], v[194:197], v[128:131]
	global_load_dwordx4 v[160:163], v160, s[98:99] offset:128
	s_waitcnt vmcnt(11)
	v_mfma_f32_16x16x32_bf16 v[124:127], v[232:235], v[194:197], v[124:127]
	ds_write_b128 v183, v[152:155] offset:4096
	v_mfma_f32_16x16x32_bf16 v[116:119], v[236:239], v[194:197], v[116:119]
	v_add_u32_e32 v152, 0xa70c000, v186
	global_load_dwordx4 v[152:155], v152, s[98:99] offset:128
	v_mfma_f32_16x16x32_bf16 v[104:107], v[224:227], v[198:201], v[104:107]
	s_waitcnt vmcnt(11)
	v_mfma_f32_16x16x32_bf16 v[100:103], v[228:231], v[198:201], v[100:103]
	ds_write_b128 v183, v[136:139] offset:6144
	v_add_u32_e32 v136, 0xa712000, v186
	v_mfma_f32_16x16x32_bf16 v[92:95], v[232:235], v[198:201], v[92:95]
	global_load_dwordx4 v[136:139], v136, s[98:99] offset:128
	v_mfma_f32_16x16x32_bf16 v[84:87], v[236:239], v[198:201], v[84:87]
	s_waitcnt vmcnt(11)
	ds_write_b128 v183, v[132:135] offset:8192
	v_mfma_f32_16x16x32_bf16 v[80:83], v[224:227], v[204:207], v[80:83]
	v_add_u32_e32 v132, 0xa718000, v186
	v_mfma_f32_16x16x32_bf16 v[76:79], v[228:231], v[204:207], v[76:79]
	global_load_dwordx4 v[132:135], v132, s[98:99] offset:128
	s_waitcnt vmcnt(11)
	v_mfma_f32_16x16x32_bf16 v[64:67], v[232:235], v[204:207], v[64:67]
	ds_write_b128 v183, v[120:123] offset:10240
	v_mfma_f32_16x16x32_bf16 v[60:63], v[236:239], v[204:207], v[60:63]
	v_add_u32_e32 v120, 0xa71e000, v186
	global_load_dwordx4 v[120:123], v120, s[98:99] offset:128
	v_mfma_f32_16x16x32_bf16 v[56:59], v[224:227], v[208:211], v[56:59]
	s_waitcnt vmcnt(11)
	v_mfma_f32_16x16x32_bf16 v[52:55], v[228:231], v[208:211], v[52:55]
	ds_write_b128 v183, v[108:111] offset:12288
	v_add_u32_e32 v108, 0xa724000, v186
	v_mfma_f32_16x16x32_bf16 v[48:51], v[232:235], v[208:211], v[48:51]
	global_load_dwordx4 v[108:111], v108, s[98:99] offset:128
	v_mfma_f32_16x16x32_bf16 v[44:47], v[236:239], v[208:211], v[44:47]
	s_waitcnt vmcnt(11)
	ds_write_b128 v183, v[96:99] offset:14336
	v_mfma_f32_16x16x32_bf16 v[40:43], v[224:227], v[212:215], v[40:43]
	v_add_u32_e32 v96, 0xa72a000, v186
	v_mfma_f32_16x16x32_bf16 v[36:39], v[228:231], v[212:215], v[36:39]
	global_load_dwordx4 v[96:99], v96, s[98:99] offset:128
	s_waitcnt vmcnt(11)
	v_mfma_f32_16x16x32_bf16 v[32:35], v[232:235], v[212:215], v[32:35]
	ds_write_b128 v183, v[148:151] offset:16384
	v_mfma_f32_16x16x32_bf16 v[28:31], v[236:239], v[212:215], v[28:31]
	v_add_u32_e32 v148, 0x1f00000, v187
	global_load_dwordx4 v[148:151], v148, s[98:99] offset:128
	v_mfma_f32_16x16x32_bf16 v[24:27], v[224:227], v[216:219], v[24:27]
	s_waitcnt vmcnt(11)
	v_mfma_f32_16x16x32_bf16 v[20:23], v[228:231], v[216:219], v[20:23]
	ds_write_b128 v183, v[88:91] offset:18432
	v_add_u32_e32 v88, 0x1f06000, v187
	v_mfma_f32_16x16x32_bf16 v[16:19], v[232:235], v[216:219], v[16:19]
	global_load_dwordx4 v[88:91], v88, s[98:99] offset:128
	v_mfma_f32_16x16x32_bf16 v[12:15], v[236:239], v[216:219], v[12:15]
	s_waitcnt vmcnt(11)
	ds_write_b128 v183, v[72:75] offset:20480
	v_mfma_f32_16x16x32_bf16 v[8:11], v[224:227], v[220:223], v[8:11]
	v_add_u32_e32 v72, 0x1f0c000, v187
	v_mfma_f32_16x16x32_bf16 v[4:7], v[228:231], v[220:223], v[4:7]
	global_load_dwordx4 v[72:75], v72, s[98:99] offset:128
	s_waitcnt vmcnt(11)
	v_mfma_f32_16x16x32_bf16 v[0:3], v[232:235], v[220:223], v[0:3]
	ds_write_b128 v183, v[68:71] offset:22528
	v_mfma_f32_16x16x32_bf16 v[112:115], v[236:239], v[220:223], v[112:115]
	v_add_u32_e32 v68, 0x1f12000, v187
	global_load_dwordx4 v[68:71], v68, s[98:99] offset:128
	v_cmp_gt_u32_e32 vcc, 0x6000, v183
	v_add_u32_e32 v182, 0xc000, v183
	v_add_u32_e32 v183, 0xffffa000, v183
	s_nop 0
	v_cndmask_b32_e32 v183, v183, v182, vcc
	s_add_u32 s0, s0, 0x80
	s_addc_u32 s1, s1, 0
	s_cmpk_lg_i32 s0, 0x280
	s_cbranch_scc1 .LBB0_400
	s_waitcnt lgkmcnt(0)
	s_barrier
	ds_read_b128 v[224:227], v184
	ds_read_b128 v[228:231], v184 offset:1024
	ds_read_b128 v[232:235], v184 offset:2048
	ds_read_b128 v[236:239], v184 offset:3072
	ds_read_b128 v[190:193], v185
	ds_read_b128 v[194:197], v185 offset:1024
	ds_read_b128 v[198:201], v185 offset:2048
	ds_read_b128 v[204:207], v185 offset:3072
	ds_read_b128 v[208:211], v185 offset:4096
	ds_read_b128 v[212:215], v185 offset:5120
	ds_read_b128 v[216:219], v185 offset:6144
	ds_read_b128 v[220:223], v185 offset:7168
	s_movk_i32 vcc_lo, 0x6000
	s_cmp_eq_u32 m0, 2
	s_cselect_b32 vcc_lo, 0xffff4000, vcc_lo
	s_add_u32 m0, m0, 1
	s_cmp_eq_u32 m0, 3
	s_cselect_b32 m0, 0, m0
	v_add_u32_e32 v185, vcc_lo, v185
	v_add_u32_e32 v184, vcc_lo, v184
	v_xor_b32_e32 v185, 64, v185
	v_xor_b32_e32 v184, 64, v184
	s_waitcnt lgkmcnt(7)
	v_mfma_f32_16x16x32_bf16 v[172:175], v[224:227], v[190:193], v[172:175]
	v_mfma_f32_16x16x32_bf16 v[164:167], v[228:231], v[190:193], v[164:167]
	v_mfma_f32_16x16x32_bf16 v[156:159], v[232:235], v[190:193], v[156:159]
	v_mfma_f32_16x16x32_bf16 v[144:147], v[236:239], v[190:193], v[144:147]
	ds_read_b128 v[190:193], v185
	s_waitcnt lgkmcnt(7)
	v_mfma_f32_16x16x32_bf16 v[140:143], v[224:227], v[194:197], v[140:143]
	v_mfma_f32_16x16x32_bf16 v[128:131], v[228:231], v[194:197], v[128:131]
	v_mfma_f32_16x16x32_bf16 v[124:127], v[232:235], v[194:197], v[124:127]
	v_mfma_f32_16x16x32_bf16 v[116:119], v[236:239], v[194:197], v[116:119]
	ds_read_b128 v[194:197], v185 offset:1024
	s_waitcnt lgkmcnt(7)
	v_mfma_f32_16x16x32_bf16 v[104:107], v[224:227], v[198:201], v[104:107]
	v_mfma_f32_16x16x32_bf16 v[100:103], v[228:231], v[198:201], v[100:103]
	v_mfma_f32_16x16x32_bf16 v[92:95], v[232:235], v[198:201], v[92:95]
	v_mfma_f32_16x16x32_bf16 v[84:87], v[236:239], v[198:201], v[84:87]
	ds_read_b128 v[198:201], v185 offset:2048
	s_waitcnt lgkmcnt(7)
	v_mfma_f32_16x16x32_bf16 v[80:83], v[224:227], v[204:207], v[80:83]
	v_mfma_f32_16x16x32_bf16 v[76:79], v[228:231], v[204:207], v[76:79]
	v_mfma_f32_16x16x32_bf16 v[64:67], v[232:235], v[204:207], v[64:67]
	v_mfma_f32_16x16x32_bf16 v[60:63], v[236:239], v[204:207], v[60:63]
	ds_read_b128 v[204:207], v185 offset:3072
	s_waitcnt lgkmcnt(7)
	v_mfma_f32_16x16x32_bf16 v[56:59], v[224:227], v[208:211], v[56:59]
	v_mfma_f32_16x16x32_bf16 v[52:55], v[228:231], v[208:211], v[52:55]
	v_mfma_f32_16x16x32_bf16 v[48:51], v[232:235], v[208:211], v[48:51]
	v_mfma_f32_16x16x32_bf16 v[44:47], v[236:239], v[208:211], v[44:47]
	ds_read_b128 v[208:211], v185 offset:4096
	s_waitcnt lgkmcnt(7)
	v_mfma_f32_16x16x32_bf16 v[40:43], v[224:227], v[212:215], v[40:43]
	v_mfma_f32_16x16x32_bf16 v[36:39], v[228:231], v[212:215], v[36:39]
	v_mfma_f32_16x16x32_bf16 v[32:35], v[232:235], v[212:215], v[32:35]
	v_mfma_f32_16x16x32_bf16 v[28:31], v[236:239], v[212:215], v[28:31]
	ds_read_b128 v[212:215], v185 offset:5120
	s_waitcnt lgkmcnt(7)
	v_mfma_f32_16x16x32_bf16 v[24:27], v[224:227], v[216:219], v[24:27]
	v_mfma_f32_16x16x32_bf16 v[20:23], v[228:231], v[216:219], v[20:23]
	v_mfma_f32_16x16x32_bf16 v[16:19], v[232:235], v[216:219], v[16:19]
	v_mfma_f32_16x16x32_bf16 v[12:15], v[236:239], v[216:219], v[12:15]
	ds_read_b128 v[216:219], v185 offset:6144
	s_waitcnt lgkmcnt(7)
	v_mfma_f32_16x16x32_bf16 v[8:11], v[224:227], v[220:223], v[8:11]
	v_mfma_f32_16x16x32_bf16 v[4:7], v[228:231], v[220:223], v[4:7]
	v_mfma_f32_16x16x32_bf16 v[0:3], v[232:235], v[220:223], v[0:3]
	v_mfma_f32_16x16x32_bf16 v[112:115], v[236:239], v[220:223], v[112:115]
	ds_read_b128 v[220:223], v185 offset:7168
	ds_read_b128 v[224:227], v184
	ds_read_b128 v[228:231], v184 offset:1024
	ds_read_b128 v[232:235], v184 offset:2048
	ds_read_b128 v[236:239], v184 offset:3072
	s_movk_i32 vcc_lo, 0x6000
	s_cmp_eq_u32 m0, 2
	s_cselect_b32 vcc_lo, 0xffff4000, vcc_lo
	s_add_u32 m0, m0, 1
	s_cmp_eq_u32 m0, 3
	s_cselect_b32 m0, 0, m0
	v_add_u32_e32 v185, vcc_lo, v185
	v_add_u32_e32 v184, vcc_lo, v184
	v_xor_b32_e32 v185, 64, v185
	v_xor_b32_e32 v184, 64, v184
	s_waitcnt lgkmcnt(0)
	v_mfma_f32_16x16x32_bf16 v[172:175], v[224:227], v[190:193], v[172:175]
	v_mfma_f32_16x16x32_bf16 v[164:167], v[228:231], v[190:193], v[164:167]
	v_mfma_f32_16x16x32_bf16 v[156:159], v[232:235], v[190:193], v[156:159]
	v_mfma_f32_16x16x32_bf16 v[144:147], v[236:239], v[190:193], v[144:147]
	v_mfma_f32_16x16x32_bf16 v[140:143], v[224:227], v[194:197], v[140:143]
	v_mfma_f32_16x16x32_bf16 v[128:131], v[228:231], v[194:197], v[128:131]
	v_mfma_f32_16x16x32_bf16 v[124:127], v[232:235], v[194:197], v[124:127]
	v_mfma_f32_16x16x32_bf16 v[116:119], v[236:239], v[194:197], v[116:119]
	v_mfma_f32_16x16x32_bf16 v[104:107], v[224:227], v[198:201], v[104:107]
	v_mfma_f32_16x16x32_bf16 v[100:103], v[228:231], v[198:201], v[100:103]
	v_mfma_f32_16x16x32_bf16 v[92:95], v[232:235], v[198:201], v[92:95]
	v_mfma_f32_16x16x32_bf16 v[84:87], v[236:239], v[198:201], v[84:87]
	v_mfma_f32_16x16x32_bf16 v[80:83], v[224:227], v[204:207], v[80:83]
	v_mfma_f32_16x16x32_bf16 v[76:79], v[228:231], v[204:207], v[76:79]
	v_mfma_f32_16x16x32_bf16 v[64:67], v[232:235], v[204:207], v[64:67]
	v_mfma_f32_16x16x32_bf16 v[60:63], v[236:239], v[204:207], v[60:63]
	v_mfma_f32_16x16x32_bf16 v[56:59], v[224:227], v[208:211], v[56:59]
	v_mfma_f32_16x16x32_bf16 v[52:55], v[228:231], v[208:211], v[52:55]
	v_mfma_f32_16x16x32_bf16 v[48:51], v[232:235], v[208:211], v[48:51]
	v_mfma_f32_16x16x32_bf16 v[44:47], v[236:239], v[208:211], v[44:47]
	v_mfma_f32_16x16x32_bf16 v[40:43], v[224:227], v[212:215], v[40:43]
	v_mfma_f32_16x16x32_bf16 v[36:39], v[228:231], v[212:215], v[36:39]
	v_mfma_f32_16x16x32_bf16 v[32:35], v[232:235], v[212:215], v[32:35]
	v_mfma_f32_16x16x32_bf16 v[28:31], v[236:239], v[212:215], v[28:31]
	v_mfma_f32_16x16x32_bf16 v[24:27], v[224:227], v[216:219], v[24:27]
	v_mfma_f32_16x16x32_bf16 v[20:23], v[228:231], v[216:219], v[20:23]
	v_mfma_f32_16x16x32_bf16 v[16:19], v[232:235], v[216:219], v[16:19]
	v_mfma_f32_16x16x32_bf16 v[12:15], v[236:239], v[216:219], v[12:15]
	v_mfma_f32_16x16x32_bf16 v[8:11], v[224:227], v[220:223], v[8:11]
	v_mfma_f32_16x16x32_bf16 v[4:7], v[228:231], v[220:223], v[4:7]
	v_mfma_f32_16x16x32_bf16 v[0:3], v[232:235], v[220:223], v[0:3]
	v_mfma_f32_16x16x32_bf16 v[112:115], v[236:239], v[220:223], v[112:115]
	v_lshrrev_b32_e32 v224, 4, v188
	v_and_b32_e32 v225, 7, v188
	v_bitop3_b32 v226, v224, v225, 3 bitop3:0x6c
	v_lshlrev_b32_e32 v227, 7, v188
	v_bfe_u32 v228, v188, 4, 2
	v_and_b32_e32 v229, 0xffffc780, v227
	v_and_b32_e32 v227, 0x2780, v227
	v_bitop3_b32 v228, v228, v225, 4 bitop3:0x36
	v_lshlrev_b32_e32 v226, 4, v226
	v_lshlrev_b32_e32 v228, 4, v228
	v_or_b32_e32 v185, v229, v226
	v_or_b32_e32 v184, v227, v226
	v_or_b32_e32 v183, v229, v228
	v_or_b32_e32 v182, v227, v228
	s_waitcnt vmcnt(0)
	s_setprio 0
	s_barrier
	s_waitcnt vmcnt(11)
	ds_write_b128 v176, v[168:171]
	s_waitcnt vmcnt(10)
	ds_write_b128 v176, v[160:163] offset:4096
	s_waitcnt vmcnt(9)
	ds_write_b128 v176, v[152:155] offset:8192
	s_waitcnt vmcnt(8)
	ds_write_b128 v176, v[136:139] offset:12288
	s_waitcnt vmcnt(7)
	ds_write_b128 v176, v[132:135] offset:16384
	s_waitcnt vmcnt(6)
	ds_write_b128 v176, v[120:123] offset:20480
	s_waitcnt vmcnt(5)
	ds_write_b128 v176, v[108:111] offset:24576
	s_waitcnt vmcnt(4)
	ds_write_b128 v176, v[96:99] offset:28672
	s_waitcnt vmcnt(3)
	ds_write_b128 v176, v[148:151] offset:32768
	s_waitcnt vmcnt(2)
	ds_write_b128 v176, v[88:91] offset:36864
	s_waitcnt vmcnt(1)
	ds_write_b128 v176, v[72:75] offset:40960
	s_waitcnt vmcnt(0)
	ds_write_b128 v176, v[68:71] offset:45056
	s_waitcnt lgkmcnt(0)
	s_barrier
	ds_read_b128 v[68:71], v185
	ds_read_b128 v[72:75], v185 offset:2048
	ds_read_b128 v[88:91], v185 offset:4096
	ds_read_b128 v[96:99], v185 offset:6144
	ds_read_b128 v[108:111], v185 offset:8192
	ds_read_b128 v[120:123], v185 offset:10240
	ds_read_b128 v[132:135], v185 offset:12288
	ds_read_b128 v[136:139], v185 offset:14336
	ds_read_b128 v[148:151], v184 offset:32768
	ds_read_b128 v[152:155], v184 offset:34816
	ds_read_b128 v[160:163], v184 offset:36864
	ds_read_b128 v[168:171], v184 offset:38912
	s_waitcnt lgkmcnt(3)
	v_mfma_f32_16x16x32_bf16 v[172:175], v[148:151], v[68:71], v[172:175]
	s_waitcnt lgkmcnt(2)
	v_mfma_f32_16x16x32_bf16 v[164:167], v[152:155], v[68:71], v[164:167]
	s_waitcnt lgkmcnt(1)
	v_mfma_f32_16x16x32_bf16 v[156:159], v[160:163], v[68:71], v[156:159]
	s_waitcnt lgkmcnt(0)
	v_mfma_f32_16x16x32_bf16 v[68:71], v[168:171], v[68:71], v[144:147]
	v_mfma_f32_16x16x32_bf16 v[140:143], v[148:151], v[72:75], v[140:143]
	v_mfma_f32_16x16x32_bf16 v[128:131], v[152:155], v[72:75], v[128:131]
	v_mfma_f32_16x16x32_bf16 v[144:147], v[160:163], v[72:75], v[124:127]
	v_mfma_f32_16x16x32_bf16 v[72:75], v[168:171], v[72:75], v[116:119]
	v_mfma_f32_16x16x32_bf16 v[64:67], v[160:163], v[96:99], v[64:67]
	v_mfma_f32_16x16x32_bf16 v[60:63], v[168:171], v[96:99], v[60:63]
	v_mfma_f32_16x16x32_bf16 v[56:59], v[148:151], v[108:111], v[56:59]
	v_mfma_f32_16x16x32_bf16 v[52:55], v[152:155], v[108:111], v[52:55]
	v_mfma_f32_16x16x32_bf16 v[48:51], v[160:163], v[108:111], v[48:51]
	v_mfma_f32_16x16x32_bf16 v[44:47], v[168:171], v[108:111], v[44:47]
	v_mfma_f32_16x16x32_bf16 v[40:43], v[148:151], v[120:123], v[40:43]
	v_mfma_f32_16x16x32_bf16 v[36:39], v[152:155], v[120:123], v[36:39]
	v_mfma_f32_16x16x32_bf16 v[32:35], v[160:163], v[120:123], v[32:35]
	v_mfma_f32_16x16x32_bf16 v[28:31], v[168:171], v[120:123], v[28:31]
	v_mfma_f32_16x16x32_bf16 v[24:27], v[148:151], v[132:135], v[24:27]
	v_mfma_f32_16x16x32_bf16 v[20:23], v[152:155], v[132:135], v[20:23]
	v_mfma_f32_16x16x32_bf16 v[16:19], v[160:163], v[132:135], v[16:19]
	v_mfma_f32_16x16x32_bf16 v[12:15], v[168:171], v[132:135], v[12:15]
	v_mfma_f32_16x16x32_bf16 v[8:11], v[148:151], v[136:139], v[8:11]
	v_mfma_f32_16x16x32_bf16 v[4:7], v[152:155], v[136:139], v[4:7]
	v_mfma_f32_16x16x32_bf16 v[0:3], v[160:163], v[136:139], v[0:3]
	v_mfma_f32_16x16x32_bf16 v[178:181], v[148:151], v[88:91], v[104:107]
	v_mfma_f32_16x16x32_bf16 v[184:187], v[152:155], v[88:91], v[100:103]
	v_mfma_f32_16x16x32_bf16 v[190:193], v[160:163], v[88:91], v[92:95]
	v_mfma_f32_16x16x32_bf16 v[194:197], v[168:171], v[88:91], v[84:87]
	v_mfma_f32_16x16x32_bf16 v[198:201], v[148:151], v[96:99], v[80:83]
	v_mfma_f32_16x16x32_bf16 v[204:207], v[152:155], v[96:99], v[76:79]
	v_mfma_f32_16x16x32_bf16 v[148:151], v[168:171], v[136:139], v[112:115]
	s_nop 1
	ds_read_b128 v[76:79], v183
	ds_read_b128 v[80:83], v183 offset:2048
	ds_read_b128 v[132:135], v183 offset:4096
	ds_read_b128 v[136:139], v183 offset:6144
	ds_read_b128 v[152:155], v183 offset:8192
	ds_read_b128 v[160:163], v183 offset:10240
	ds_read_b128 v[168:171], v183 offset:12288
	ds_read_b128 v[208:211], v183 offset:14336
	ds_read_b128 v[212:215], v182 offset:32768
	ds_read_b128 v[216:219], v182 offset:34816
	ds_read_b128 v[220:223], v182 offset:36864
	ds_read_b128 v[224:227], v182 offset:38912
	s_waitcnt lgkmcnt(3)
	v_mfma_f32_16x16x32_bf16 v[124:127], v[212:215], v[76:79], v[172:175]
	s_movk_i32 s0, 0xfff
	s_waitcnt lgkmcnt(2)
	v_mfma_f32_16x16x32_bf16 v[120:123], v[216:219], v[76:79], v[164:167]
	s_waitcnt lgkmcnt(1)
	v_mfma_f32_16x16x32_bf16 v[116:119], v[220:223], v[76:79], v[156:159]
	s_waitcnt lgkmcnt(0)
	v_mfma_f32_16x16x32_bf16 v[112:115], v[224:227], v[76:79], v[68:71]
	v_mfma_f32_16x16x32_bf16 v[108:111], v[212:215], v[80:83], v[140:143]
	v_mfma_f32_16x16x32_bf16 v[104:107], v[216:219], v[80:83], v[128:131]
	v_mfma_f32_16x16x32_bf16 v[100:103], v[220:223], v[80:83], v[144:147]
	v_mfma_f32_16x16x32_bf16 v[96:99], v[224:227], v[80:83], v[72:75]
	v_mfma_f32_16x16x32_bf16 v[92:95], v[212:215], v[132:135], v[178:181]
	v_mfma_f32_16x16x32_bf16 v[88:91], v[216:219], v[132:135], v[184:187]
	v_mfma_f32_16x16x32_bf16 v[84:87], v[220:223], v[132:135], v[190:193]
	v_mfma_f32_16x16x32_bf16 v[80:83], v[224:227], v[132:135], v[194:197]
	v_mov_b32_e32 v132, v188
	v_mfma_f32_16x16x32_bf16 v[76:79], v[212:215], v[136:139], v[198:201]
	v_mfma_f32_16x16x32_bf16 v[72:75], v[216:219], v[136:139], v[204:207]
	v_mfma_f32_16x16x32_bf16 v[68:71], v[220:223], v[136:139], v[64:67]
	v_mfma_f32_16x16x32_bf16 v[64:67], v[224:227], v[136:139], v[60:63]
	v_mov_b32_e32 v137, v188
	v_mfma_f32_16x16x32_bf16 v[60:63], v[212:215], v[152:155], v[56:59]
	v_and_b32_e32 v143, 15, v137
	v_and_or_b32 v136, v132, 64, s8
	v_and_b32_e32 v176, 48, v137
	v_mfma_f32_16x16x32_bf16 v[56:59], v[216:219], v[152:155], v[52:55]
	v_mfma_f32_16x16x32_bf16 v[52:55], v[220:223], v[152:155], v[48:51]
	v_mfma_f32_16x16x32_bf16 v[48:51], v[224:227], v[152:155], v[44:47]
	v_mfma_f32_16x16x32_bf16 v[44:47], v[212:215], v[160:163], v[40:43]
	v_mfma_f32_16x16x32_bf16 v[40:43], v[216:219], v[160:163], v[36:39]
	v_mfma_f32_16x16x32_bf16 v[36:39], v[224:227], v[160:163], v[28:31]
	s_nop 2
	v_and_b32_e32 v28, 0xffffff80, v132
	v_add_u32_e32 v144, s9, v28
	v_or_b32_e32 v145, v144, v143
	v_mfma_f32_16x16x32_bf16 v[28:31], v[216:219], v[168:171], v[20:23]
	v_cmp_lt_i32_e32 vcc, s0, v144
	s_mov_b32 s0, 0x2aaaaaab
	v_and_b32_e32 v142, 0x380, v144
	v_lshlrev_b32_e32 v20, 3, v145
	v_ashrrev_i32_e32 v21, 31, v20
	v_lshl_add_u64 v[128:129], v[20:21], 2, s[4:5]
	global_load_dwordx2 v[138:139], v[128:129], off offset:16
	s_nop 0
	global_load_dwordx4 v[128:131], v[128:129], off
	v_mfma_f32_16x16x32_bf16 v[20:23], v[220:223], v[168:171], v[16:19]
	v_mfma_f32_16x16x32_bf16 v[16:19], v[224:227], v[168:171], v[12:15]
	s_nop 2
	v_mul_hi_i32 v12, v136, s0
	v_lshrrev_b32_e32 v13, 31, v12
	v_lshrrev_b32_e32 v12, 5, v12
	v_add_u32_e32 v132, v12, v13
	s_movk_i32 s0, 0xc0
	v_mfma_f32_16x16x32_bf16 v[12:15], v[216:219], v[208:211], v[4:7]
	s_nop 2
	v_mul_lo_u32 v4, v132, s0
	v_sub_u32_e32 v4, v136, v4
	v_cmp_eq_u32_e64 s[0:1], s19, v4
	s_and_b64 s[40:41], s[0:1], vcc
	v_readlane_b32 s0, v255, 45
	v_mfma_f32_16x16x32_bf16 v[32:35], v[220:223], v[160:163], v[32:35]
	v_readlane_b32 s1, v255, 46
	v_mfma_f32_16x16x32_bf16 v[24:27], v[212:215], v[168:171], v[24:27]
	s_nop 0
	v_lshl_add_u64 v[134:135], s[0:1], 0, v[176:177]
	v_readlane_b32 s0, v255, 47
	v_readlane_b32 s1, v255, 48
	v_mfma_f32_16x16x32_bf16 v[8:11], v[212:215], v[208:211], v[8:11]
	s_nop 0
	v_lshl_add_u64 v[132:133], s[0:1], 0, v[176:177]
	v_mfma_f32_16x16x32_bf16 v[0:3], v[220:223], v[208:211], v[0:3]
	v_mfma_f32_16x16x32_bf16 v[4:7], v[224:227], v[208:211], v[148:151]
	s_and_saveexec_b64 s[0:1], s[40:41]
	s_cbranch_execz .LBB0_403
	v_or_b32_e32 v140, v142, v143
	v_lshlrev_b32_e32 v176, 7, v140
	v_lshl_add_u64 v[154:155], v[134:135], 0, v[176:177]
	v_lshl_add_u64 v[156:157], v[132:133], 0, v[176:177]
	global_load_dwordx4 v[146:149], v[154:155], off
	global_load_dwordx4 v[150:153], v[156:157], off
	global_load_dwordx4 v[228:231], v[154:155], off offset:64
	global_load_dwordx4 v[232:235], v[156:157], off offset:64
	s_waitcnt vmcnt(2)
	v_pk_mul_f32 v[158:159], v[124:125], v[150:151]
	v_pk_mul_f32 v[140:141], v[116:117], v[150:151]
	v_mul_f32_e32 v150, v126, v148
	v_mul_f32_e32 v160, v118, v152
	v_mul_f32_e32 v162, v126, v152
	v_mul_f32_e32 v148, v118, v148
	v_mov_b32_e32 v118, v127
	v_mov_b32_e32 v152, v149
	v_mov_b32_e32 v126, v119
	v_pk_mul_f32 v[164:165], v[118:119], v[152:153]
	v_pk_mul_f32 v[118:119], v[126:127], v[152:153]
	v_mov_b32_e32 v151, v164
	v_mov_b32_e32 v161, v165
	v_mov_b32_e32 v149, v118
	v_mov_b32_e32 v163, v119
	v_pk_fma_f32 v[124:125], v[124:125], v[146:147], v[140:141] neg_lo:[0,0,1] neg_hi:[0,0,1]
	v_pk_add_f32 v[140:141], v[150:151], v[160:161] neg_lo:[0,1] neg_hi:[0,1]
	v_pk_fma_f32 v[116:117], v[116:117], v[146:147], v[158:159]
	v_pk_add_f32 v[118:119], v[148:149], v[162:163]
	s_waitcnt vmcnt(0)
	v_mul_f32_e32 v154, v122, v230
	s_waitcnt vmcnt(0)
	v_mul_f32_e32 v156, v114, v234
	v_mul_f32_e32 v158, v122, v234
	v_mul_f32_e32 v230, v114, v230
	v_mov_b32_e32 v114, v123
	v_mov_b32_e32 v234, v231
	v_pk_mul_f32 v[160:161], v[114:115], v[234:235]
	v_mov_b32_e32 v122, v115
	v_pk_mul_f32 v[126:127], v[120:121], v[232:233]
	v_pk_mul_f32 v[232:233], v[112:113], v[232:233]
	v_mov_b32_e32 v155, v160
	v_mov_b32_e32 v157, v161
	v_pk_mul_f32 v[114:115], v[122:123], v[234:235]
	v_pk_fma_f32 v[120:121], v[120:121], v[228:229], v[232:233] neg_lo:[0,0,1] neg_hi:[0,0,1]
	v_pk_add_f32 v[232:233], v[154:155], v[156:157] neg_lo:[0,1] neg_hi:[0,1]
	v_mov_b32_e32 v231, v114
	v_mov_b32_e32 v159, v115
	v_pk_fma_f32 v[112:113], v[112:113], v[228:229], v[126:127]
	v_pk_add_f32 v[114:115], v[230:231], v[158:159]
	v_mov_b32_e32 v122, v232
	v_mov_b32_e32 v123, v233
	v_mov_b32_e32 v126, v140
	v_mov_b32_e32 v127, v141
.LBB0_403:
	s_or_b64 exec, exec, s[0:1]
	s_waitcnt vmcnt(0)
	v_add_f32_e32 v128, 0, v128
	v_add_f32_e32 v128, v128, v129
	v_add_f32_e32 v128, v128, v130
	v_add_f32_e32 v128, v128, v131
	v_add_f32_e32 v128, v128, v138
	v_add_f32_e32 v128, v128, v139
	v_fmamk_f32 v128, v128, 0x3b2aaaab, v252
	v_mul_f32_e32 v129, 0x4b800000, v128
	v_cmp_gt_f32_e32 vcc, s25, v128
	v_cmp_lt_i32_e64 s[0:1], v189, v202
	v_lshrrev_b32_e32 v140, 4, v137
	v_cndmask_b32_e32 v128, v128, v129, vcc
	v_rsq_f32_e32 v128, v128
	v_cndmask_b32_e64 v129, v203, v189, s[0:1]
	v_lshlrev_b32_e32 v130, 2, v129
	v_lshlrev_b32_e32 v141, 2, v140
	v_mul_f32_e32 v129, 0x45800000, v128
	v_cndmask_b32_e32 v128, v128, v129, vcc
	v_ashrrev_i32_e32 v137, 31, v136
	v_and_b32_e32 v140, 1, v140
	v_mul_f32_e32 v138, 0x3dd53b94, v128
	v_mov_b64_e32 v[128:129], s[22:23]
	s_movk_i32 s8, 0xc00
	v_mad_i64_i32 v[146:147], s[0:1], v145, s8, v[128:129]
	v_lshlrev_b64 v[128:129], 1, v[136:137]
	v_pk_mul_f32 v[126:127], v[138:139], v[126:127] op_sel_hi:[0,1]
	v_pk_mul_f32 v[124:125], v[138:139], v[124:125] op_sel_hi:[0,1]
	v_pk_mul_f32 v[122:123], v[138:139], v[122:123] op_sel_hi:[0,1]
	v_pk_mul_f32 v[120:121], v[138:139], v[120:121] op_sel_hi:[0,1]
	v_cmp_eq_u32_e32 vcc, 0, v140
	v_and_b32_e32 v131, 8, v141
	v_lshl_add_u64 v[136:137], v[146:147], 0, v[128:129]
	s_nop 0
	s_nop 0
	s_nop 0
	s_nop 0
	s_nop 0
	s_nop 0
	s_nop 0
	s_nop 0
	v_lshlrev_b32_e32 v176, 1, v131
	s_waitcnt lgkmcnt(0)
	s_nop 0
	v_mov_b32_e32 v139, v120
	s_nop 1
	v_permlane16_swap_b32_e32 v124, v139
	s_waitcnt lgkmcnt(0)
	s_nop 0
	v_mov_b32_e32 v120, v125
	v_mov_b32_e32 v125, v121
	s_nop 1
	v_permlane16_swap_b32_e32 v120, v125
	s_waitcnt lgkmcnt(0)
	s_nop 0
	v_mov_b32_e32 v121, v126
	v_mov_b32_e32 v126, v122
	s_nop 1
	v_permlane16_swap_b32_e32 v121, v126
	s_waitcnt lgkmcnt(0)
	s_nop 0
	v_mov_b32_e32 v122, v127
	s_nop 1
	v_permlane16_swap_b32_e32 v122, v123
	v_cvt_pk_bf16_f32 v120, v124, v120
	v_cvt_pk_bf16_f32 v121, v121, v122
	v_cvt_pk_bf16_f32 v122, v139, v125
	v_lshlrev_b32_e32 v124, 5, v140
	v_mov_b32_e32 v125, v177
	v_cvt_pk_bf16_f32 v123, v126, v123
	v_lshl_add_u64 v[126:127], v[136:137], 0, v[124:125]
	v_lshl_add_u64 v[126:127], v[126:127], 0, v[176:177]
	v_pk_mul_f32 v[118:119], v[138:139], v[118:119] op_sel_hi:[0,1]
	v_pk_mul_f32 v[116:117], v[138:139], v[116:117] op_sel_hi:[0,1]
	v_pk_mul_f32 v[114:115], v[138:139], v[114:115] op_sel_hi:[0,1]
	v_pk_mul_f32 v[112:113], v[138:139], v[112:113] op_sel_hi:[0,1]
	global_store_dwordx4 v[126:127], v[120:123], off
	s_nop 0
	v_cndmask_b32_e32 v127, v119, v115, vcc
	s_nop 0
	s_nop 0
	s_nop 0
	s_nop 0
	s_nop 0
	ds_bpermute_b32 v127, v130, v127
	v_mov_b64_e32 v[120:121], s[34:35]
	v_mad_i64_i32 v[120:121], s[0:1], v145, s8, v[120:121]
	v_lshl_add_u64 v[120:121], v[120:121], 0, v[128:129]
	s_waitcnt lgkmcnt(1)
	s_nop 0
	v_mov_b32_e32 v122, v112
	s_nop 1
	v_permlane16_swap_b32_e32 v116, v122
	s_waitcnt lgkmcnt(1)
	s_nop 0
	v_mov_b32_e32 v112, v117
	v_mov_b32_e32 v117, v113
	s_nop 1
	v_permlane16_swap_b32_e32 v112, v117
	s_waitcnt lgkmcnt(1)
	s_nop 0
	v_mov_b32_e32 v113, v118
	v_mov_b32_e32 v118, v114
	s_nop 1
	v_permlane16_swap_b32_e32 v113, v118
	s_waitcnt lgkmcnt(0)
	v_cndmask_b32_e32 v114, v127, v119, vcc
	v_cvt_pk_bf16_f32 v112, v116, v112
	v_cvt_pk_bf16_f32 v113, v113, v114
	v_cvt_pk_bf16_f32 v114, v122, v117
	v_lshl_add_u64 v[116:117], v[120:121], 0, v[124:125]
	v_cndmask_b32_e32 v115, v115, v127, vcc
	v_lshl_add_u64 v[116:117], v[116:117], 0, v[176:177]
	s_mov_b32 s0, 0x3900000
	v_cvt_pk_bf16_f32 v115, v118, v115
	v_add_co_u32_e64 v116, s[0:1], s0, v116
	v_or_b32_e32 v118, 16, v143
	s_nop 0
	v_addc_co_u32_e64 v117, s[0:1], 0, v117, s[0:1]
	v_or_b32_e32 v120, v144, v118
	global_store_dwordx4 v[116:117], v[112:115], off offset:64
	s_nop 1
	v_lshlrev_b32_e32 v112, 3, v120
	v_ashrrev_i32_e32 v113, 31, v112
	v_lshl_add_u64 v[112:113], v[112:113], 2, s[4:5]
	global_load_dwordx4 v[190:193], v[112:113], off offset:512
	global_load_dwordx2 v[194:195], v[112:113], off offset:528
	global_load_dwordx4 v[196:199], v[112:113], off offset:1024
	global_load_dwordx2 v[200:201], v[112:113], off offset:1040
	global_load_dwordx4 v[204:207], v[112:113], off offset:1536
	global_load_dwordx2 v[208:209], v[112:113], off offset:1552
	global_load_dwordx4 v[210:213], v[112:113], off offset:2048
	global_load_dwordx2 v[214:215], v[112:113], off offset:2064
	global_load_dwordx4 v[216:219], v[112:113], off offset:2560
	global_load_dwordx2 v[220:221], v[112:113], off offset:2576
	global_load_dwordx4 v[222:225], v[112:113], off offset:3072
	global_load_dwordx2 v[226:227], v[112:113], off offset:3088
	global_load_dwordx2 v[116:117], v[112:113], off offset:16
	s_nop 0
	global_load_dwordx4 v[112:115], v[112:113], off
	s_and_saveexec_b64 s[0:1], s[40:41]
	s_cbranch_execz .LBB0_405
	v_or_b32_e32 v118, v142, v118
	v_lshlrev_b32_e32 v118, 7, v118
	v_mov_b32_e32 v119, v177
	v_lshl_add_u64 v[126:127], v[134:135], 0, v[118:119]
	v_lshl_add_u64 v[146:147], v[132:133], 0, v[118:119]
	global_load_dwordx4 v[122:125], v[126:127], off
	global_load_dwordx4 v[136:139], v[146:147], off
	global_load_dwordx4 v[228:231], v[126:127], off offset:64
	global_load_dwordx4 v[232:235], v[146:147], off offset:64
	s_waitcnt vmcnt(2)
	v_pk_mul_f32 v[148:149], v[108:109], v[136:137]
	v_pk_mul_f32 v[118:119], v[100:101], v[136:137]
	v_mul_f32_e32 v136, v110, v124
	v_mul_f32_e32 v150, v102, v138
	v_mul_f32_e32 v152, v110, v138
	v_mul_f32_e32 v124, v102, v124
	v_mov_b32_e32 v102, v111
	v_mov_b32_e32 v138, v125
	v_mov_b32_e32 v110, v103
	v_pk_mul_f32 v[154:155], v[102:103], v[138:139]
	v_pk_mul_f32 v[102:103], v[110:111], v[138:139]
	v_mov_b32_e32 v137, v154
	v_mov_b32_e32 v151, v155
	v_mov_b32_e32 v125, v102
	v_mov_b32_e32 v153, v103
	v_pk_fma_f32 v[108:109], v[108:109], v[122:123], v[118:119] neg_lo:[0,0,1] neg_hi:[0,0,1]
	v_pk_add_f32 v[118:119], v[136:137], v[150:151] neg_lo:[0,1] neg_hi:[0,1]
	v_pk_fma_f32 v[100:101], v[100:101], v[122:123], v[148:149]
	v_pk_add_f32 v[102:103], v[124:125], v[152:153]
	s_waitcnt vmcnt(0)
	v_pk_mul_f32 v[110:111], v[104:105], v[232:233]
	v_pk_mul_f32 v[126:127], v[96:97], v[232:233]
	v_mul_f32_e32 v232, v106, v230
	v_mul_f32_e32 v146, v98, v234
	v_mul_f32_e32 v148, v106, v234
	v_mul_f32_e32 v230, v98, v230
	v_mov_b32_e32 v98, v107
	v_mov_b32_e32 v234, v231
	v_pk_mul_f32 v[150:151], v[98:99], v[234:235]
	v_mov_b32_e32 v106, v99
	v_mov_b32_e32 v233, v150
	v_mov_b32_e32 v147, v151
	v_pk_mul_f32 v[98:99], v[106:107], v[234:235]
	v_pk_fma_f32 v[104:105], v[104:105], v[228:229], v[126:127] neg_lo:[0,0,1] neg_hi:[0,0,1]
	v_pk_add_f32 v[126:127], v[232:233], v[146:147] neg_lo:[0,1] neg_hi:[0,1]
	v_mov_b32_e32 v231, v98
	v_mov_b32_e32 v149, v99
	v_pk_fma_f32 v[96:97], v[96:97], v[228:229], v[110:111]
	v_pk_add_f32 v[98:99], v[230:231], v[148:149]
	v_mov_b32_e32 v106, v126
	v_mov_b32_e32 v107, v127
	v_mov_b32_e32 v110, v118
	v_mov_b32_e32 v111, v119
.LBB0_405:
	s_or_b64 exec, exec, s[0:1]
	s_waitcnt vmcnt(0)
	v_add_f32_e32 v112, 0, v112
	v_add_f32_e32 v112, v112, v113
	v_add_f32_e32 v112, v112, v114
	v_add_f32_e32 v112, v112, v115
	v_add_f32_e32 v112, v112, v116
	v_add_f32_e32 v112, v112, v117
	v_fmamk_f32 v112, v112, 0x3b2aaaab, v252
	v_mul_f32_e32 v113, 0x4b800000, v112
	v_cmp_gt_f32_e64 s[0:1], s25, v112
	v_lshlrev_b32_e32 v115, 4, v140
	s_nop 0
	v_cndmask_b32_e64 v112, v112, v113, s[0:1]
	v_rsq_f32_e32 v114, v112
	v_mov_b64_e32 v[112:113], s[22:23]
	v_mul_f32_e32 v116, 0x45800000, v114
	v_cndmask_b32_e64 v114, v114, v116, s[0:1]
	v_mul_f32_e32 v114, 0x3dd53b94, v114
	v_pk_mul_f32 v[108:109], v[114:115], v[108:109] op_sel_hi:[0,1]
	v_pk_mul_f32 v[104:105], v[114:115], v[104:105] op_sel_hi:[0,1]
	v_pk_mul_f32 v[110:111], v[114:115], v[110:111] op_sel_hi:[0,1]
	v_pk_mul_f32 v[106:107], v[114:115], v[106:107] op_sel_hi:[0,1]
	s_nop 0
	s_nop 0
	s_nop 0
	s_nop 0
	s_nop 0
	s_nop 0
	s_nop 0
	s_nop 0
	v_mad_i64_i32 v[112:113], s[0:1], v120, s8, v[112:113]
	s_waitcnt lgkmcnt(0)
	s_nop 0
	s_nop 1
	v_permlane16_swap_b32_e32 v108, v104
	s_waitcnt lgkmcnt(0)
	s_nop 0
	s_nop 1
	v_permlane16_swap_b32_e32 v109, v105
	v_lshl_add_u64 v[112:113], v[112:113], 0, v[128:129]
	s_waitcnt lgkmcnt(0)
	s_nop 0
	v_mov_b32_e32 v116, v106
	s_nop 1
	v_permlane16_swap_b32_e32 v110, v116
	s_waitcnt lgkmcnt(0)
	s_nop 0
	v_cvt_pk_bf16_f32 v106, v108, v109
	v_cvt_pk_bf16_f32 v108, v104, v105
	v_lshlrev_b32_e32 v104, 1, v115
	v_mov_b32_e32 v105, v177
	v_mov_b32_e32 v117, v107
	s_nop 1
	v_permlane16_swap_b32_e32 v111, v117
	v_cvt_pk_bf16_f32 v107, v110, v111
	v_lshl_add_u64 v[110:111], v[112:113], 0, v[104:105]
	v_cvt_pk_bf16_f32 v109, v116, v117
	v_lshl_add_u64 v[110:111], v[110:111], 0, v[176:177]
	v_pk_mul_f32 v[102:103], v[114:115], v[102:103] op_sel_hi:[0,1]
	v_pk_mul_f32 v[100:101], v[114:115], v[100:101] op_sel_hi:[0,1]
	v_pk_mul_f32 v[98:99], v[114:115], v[98:99] op_sel_hi:[0,1]
	v_pk_mul_f32 v[96:97], v[114:115], v[96:97] op_sel_hi:[0,1]
	global_store_dwordx4 v[110:111], v[106:109], off
	s_nop 0
	v_cndmask_b32_e32 v111, v103, v99, vcc
	s_nop 0
	s_nop 0
	s_nop 0
	s_nop 0
	s_nop 0
	ds_bpermute_b32 v111, v130, v111
	v_mov_b64_e32 v[106:107], s[34:35]
	v_mad_i64_i32 v[106:107], s[0:1], v120, s8, v[106:107]
	v_lshl_add_u64 v[106:107], v[106:107], 0, v[128:129]
	s_waitcnt lgkmcnt(1)
	s_nop 0
	v_mov_b32_e32 v108, v96
	s_nop 1
	v_permlane16_swap_b32_e32 v100, v108
	s_waitcnt lgkmcnt(1)
	s_nop 0
	v_mov_b32_e32 v96, v101
	v_mov_b32_e32 v101, v97
	s_nop 1
	v_permlane16_swap_b32_e32 v96, v101
	s_waitcnt lgkmcnt(1)
	s_nop 0
	v_mov_b32_e32 v97, v102
	v_mov_b32_e32 v102, v98
	s_nop 1
	v_permlane16_swap_b32_e32 v97, v102
	s_waitcnt lgkmcnt(0)
	v_cndmask_b32_e32 v98, v111, v103, vcc
	v_cvt_pk_bf16_f32 v96, v100, v96
	v_cvt_pk_bf16_f32 v97, v97, v98
	v_cvt_pk_bf16_f32 v98, v108, v101
	v_lshl_add_u64 v[100:101], v[106:107], 0, v[104:105]
	v_cndmask_b32_e32 v99, v99, v111, vcc
	v_lshl_add_u64 v[100:101], v[100:101], 0, v[176:177]
	s_mov_b32 s0, 0x3900000
	v_cvt_pk_bf16_f32 v99, v102, v99
	v_add_co_u32_e64 v100, s[0:1], s0, v100
	v_or_b32_e32 v102, 32, v143
	s_nop 0
	v_addc_co_u32_e64 v101, s[0:1], 0, v101, s[0:1]
	v_or_b32_e32 v106, v144, v102
	global_store_dwordx4 v[100:101], v[96:99], off offset:64
	s_nop 1
	v_mov_b64_e32 v[100:101], v[194:195]
	v_mov_b64_e32 v[96:97], v[190:191]
	v_mov_b64_e32 v[98:99], v[192:193]
	s_and_saveexec_b64 s[0:1], s[40:41]
	s_cbranch_execz .LBB0_407
	v_or_b32_e32 v102, v142, v102
	v_lshlrev_b32_e32 v102, 7, v102
	v_mov_b32_e32 v103, v177
	v_lshl_add_u64 v[116:117], v[134:135], 0, v[102:103]
	v_lshl_add_u64 v[118:119], v[132:133], 0, v[102:103]
	global_load_dwordx4 v[108:111], v[116:117], off
	global_load_dwordx4 v[112:115], v[118:119], off
	global_load_dwordx4 v[228:231], v[116:117], off offset:64
	global_load_dwordx4 v[232:235], v[118:119], off offset:64
	s_waitcnt vmcnt(2)
	v_pk_mul_f32 v[120:121], v[92:93], v[112:113]
	v_pk_mul_f32 v[102:103], v[84:85], v[112:113]
	v_mul_f32_e32 v112, v94, v110
	v_mul_f32_e32 v122, v86, v114
	v_mul_f32_e32 v124, v94, v114
	v_mul_f32_e32 v110, v86, v110
	v_mov_b32_e32 v86, v95
	v_mov_b32_e32 v114, v111
	v_mov_b32_e32 v94, v87
	v_pk_mul_f32 v[126:127], v[86:87], v[114:115]
	v_pk_mul_f32 v[86:87], v[94:95], v[114:115]
	v_mov_b32_e32 v113, v126
	v_mov_b32_e32 v123, v127
	v_mov_b32_e32 v111, v86
	v_mov_b32_e32 v125, v87
	v_pk_fma_f32 v[92:93], v[92:93], v[108:109], v[102:103] neg_lo:[0,0,1] neg_hi:[0,0,1]
	v_pk_add_f32 v[102:103], v[112:113], v[122:123] neg_lo:[0,1] neg_hi:[0,1]
	v_pk_fma_f32 v[84:85], v[84:85], v[108:109], v[120:121]
	v_pk_add_f32 v[86:87], v[110:111], v[124:125]
	s_waitcnt vmcnt(0)
	v_mul_f32_e32 v116, v90, v230
	s_waitcnt vmcnt(0)
	v_mul_f32_e32 v118, v82, v234
	v_mul_f32_e32 v120, v90, v234
	v_mul_f32_e32 v230, v82, v230
	v_mov_b32_e32 v82, v91
	v_mov_b32_e32 v234, v231
	v_pk_mul_f32 v[122:123], v[82:83], v[234:235]
	v_mov_b32_e32 v90, v83
	v_pk_mul_f32 v[94:95], v[88:89], v[232:233]
	v_pk_mul_f32 v[232:233], v[80:81], v[232:233]
	v_mov_b32_e32 v117, v122
	v_mov_b32_e32 v119, v123
	v_pk_mul_f32 v[82:83], v[90:91], v[234:235]
	v_pk_fma_f32 v[88:89], v[88:89], v[228:229], v[232:233] neg_lo:[0,0,1] neg_hi:[0,0,1]
	v_pk_add_f32 v[232:233], v[116:117], v[118:119] neg_lo:[0,1] neg_hi:[0,1]
	v_mov_b32_e32 v231, v82
	v_mov_b32_e32 v121, v83
	v_pk_fma_f32 v[80:81], v[80:81], v[228:229], v[94:95]
	v_pk_add_f32 v[82:83], v[230:231], v[120:121]
	v_mov_b32_e32 v90, v232
	v_mov_b32_e32 v91, v233
	v_mov_b32_e32 v94, v102
	v_mov_b32_e32 v95, v103
.LBB0_407:
	s_or_b64 exec, exec, s[0:1]
	v_add_f32_e32 v96, 0, v96
	v_add_f32_e32 v96, v96, v97
	v_add_f32_e32 v96, v96, v98
	v_add_f32_e32 v96, v96, v99
	v_add_f32_e32 v96, v96, v100
	v_add_f32_e32 v96, v96, v101
	v_fmamk_f32 v96, v96, 0x3b2aaaab, v252
	v_mul_f32_e32 v97, 0x4b800000, v96
	v_cmp_gt_f32_e64 s[0:1], s25, v96
	s_nop 1
	v_cndmask_b32_e64 v96, v96, v97, s[0:1]
	v_rsq_f32_e32 v98, v96
	v_mov_b64_e32 v[96:97], s[22:23]
	v_mul_f32_e32 v99, 0x45800000, v98
	v_cndmask_b32_e64 v98, v98, v99, s[0:1]
	v_mul_f32_e32 v98, 0x3dd53b94, v98
	v_pk_mul_f32 v[94:95], v[98:99], v[94:95] op_sel_hi:[0,1]
	v_pk_mul_f32 v[92:93], v[98:99], v[92:93] op_sel_hi:[0,1]
	v_pk_mul_f32 v[90:91], v[98:99], v[90:91] op_sel_hi:[0,1]
	v_pk_mul_f32 v[88:89], v[98:99], v[88:89] op_sel_hi:[0,1]
	s_nop 0
	s_nop 0
	s_nop 0
	s_nop 0
	s_nop 0
	s_nop 0
	s_nop 0
	s_nop 0
	v_mad_i64_i32 v[96:97], s[0:1], v106, s8, v[96:97]
	v_lshl_add_u64 v[96:97], v[96:97], 0, v[128:129]
	s_waitcnt lgkmcnt(0)
	s_nop 0
	v_mov_b32_e32 v99, v88
	s_nop 1
	v_permlane16_swap_b32_e32 v92, v99
	s_waitcnt lgkmcnt(0)
	s_nop 0
	v_mov_b32_e32 v88, v93
	v_mov_b32_e32 v93, v89
	s_nop 1
	v_permlane16_swap_b32_e32 v88, v93
	s_waitcnt lgkmcnt(0)
	s_nop 0
	v_mov_b32_e32 v89, v94
	v_mov_b32_e32 v94, v90
	s_nop 1
	v_permlane16_swap_b32_e32 v89, v94
	s_waitcnt lgkmcnt(0)
	s_nop 0
	v_mov_b32_e32 v90, v95
	s_nop 1
	v_permlane16_swap_b32_e32 v90, v91
	v_cvt_pk_bf16_f32 v88, v92, v88
	v_cvt_pk_bf16_f32 v89, v89, v90
	v_cvt_pk_bf16_f32 v90, v99, v93
	v_lshl_add_u64 v[92:93], v[96:97], 0, v[104:105]
	v_cvt_pk_bf16_f32 v91, v94, v91
	v_lshl_add_u64 v[92:93], v[92:93], 0, v[176:177]
	v_pk_mul_f32 v[86:87], v[98:99], v[86:87] op_sel_hi:[0,1]
	v_pk_mul_f32 v[84:85], v[98:99], v[84:85] op_sel_hi:[0,1]
	v_pk_mul_f32 v[82:83], v[98:99], v[82:83] op_sel_hi:[0,1]
	v_pk_mul_f32 v[80:81], v[98:99], v[80:81] op_sel_hi:[0,1]
	global_store_dwordx4 v[92:93], v[88:91], off
	s_nop 0
	v_cndmask_b32_e32 v93, v87, v83, vcc
	s_nop 0
	s_nop 0
	s_nop 0
	s_nop 0
	s_nop 0
	ds_bpermute_b32 v93, v130, v93
	v_mov_b64_e32 v[88:89], s[34:35]
	v_mad_i64_i32 v[88:89], s[0:1], v106, s8, v[88:89]
	v_lshl_add_u64 v[88:89], v[88:89], 0, v[128:129]
	s_waitcnt lgkmcnt(1)
	s_nop 0
	v_mov_b32_e32 v90, v80
	s_nop 1
	v_permlane16_swap_b32_e32 v84, v90
	s_waitcnt lgkmcnt(1)
	s_nop 0
	v_mov_b32_e32 v80, v85
	v_mov_b32_e32 v85, v81
	s_nop 1
	v_permlane16_swap_b32_e32 v80, v85
	s_waitcnt lgkmcnt(1)
	s_nop 0
	v_mov_b32_e32 v81, v86
	v_mov_b32_e32 v86, v82
	s_nop 1
	v_permlane16_swap_b32_e32 v81, v86
	s_waitcnt lgkmcnt(0)
	v_cndmask_b32_e32 v82, v93, v87, vcc
	v_cvt_pk_bf16_f32 v80, v84, v80
	v_cvt_pk_bf16_f32 v81, v81, v82
	v_cvt_pk_bf16_f32 v82, v90, v85
	v_lshl_add_u64 v[84:85], v[88:89], 0, v[104:105]
	v_cndmask_b32_e32 v83, v83, v93, vcc
	v_lshl_add_u64 v[84:85], v[84:85], 0, v[176:177]
	s_mov_b32 s0, 0x3900000
	v_cvt_pk_bf16_f32 v83, v86, v83
	v_add_co_u32_e64 v84, s[0:1], s0, v84
	v_or_b32_e32 v86, 48, v143
	s_nop 0
	v_addc_co_u32_e64 v85, s[0:1], 0, v85, s[0:1]
	v_or_b32_e32 v88, v144, v86
	global_store_dwordx4 v[84:85], v[80:83], off offset:64
	s_nop 1
	v_mov_b64_e32 v[84:85], v[200:201]
	v_mov_b64_e32 v[80:81], v[196:197]
	v_mov_b64_e32 v[82:83], v[198:199]
	s_and_saveexec_b64 s[0:1], s[40:41]
	s_cbranch_execz .LBB0_409
	v_or_b32_e32 v86, v142, v86
	v_lshlrev_b32_e32 v86, 7, v86
	v_mov_b32_e32 v87, v177
	v_lshl_add_u64 v[98:99], v[134:135], 0, v[86:87]
	v_lshl_add_u64 v[100:101], v[132:133], 0, v[86:87]
	global_load_dwordx4 v[90:93], v[98:99], off
	global_load_dwordx4 v[94:97], v[100:101], off
	global_load_dwordx4 v[228:231], v[98:99], off offset:64
	global_load_dwordx4 v[232:235], v[100:101], off offset:64
	s_waitcnt vmcnt(2)
	v_pk_mul_f32 v[102:103], v[76:77], v[94:95]
	v_pk_mul_f32 v[86:87], v[68:69], v[94:95]
	v_mul_f32_e32 v94, v78, v92
	v_mul_f32_e32 v106, v70, v96
	v_mul_f32_e32 v108, v78, v96
	v_mul_f32_e32 v92, v70, v92
	v_mov_b32_e32 v70, v79
	v_mov_b32_e32 v96, v93
	v_mov_b32_e32 v78, v71
	v_pk_mul_f32 v[110:111], v[70:71], v[96:97]
	v_pk_mul_f32 v[70:71], v[78:79], v[96:97]
	v_mov_b32_e32 v95, v110
	v_mov_b32_e32 v107, v111
	v_mov_b32_e32 v93, v70
	v_mov_b32_e32 v109, v71
	v_pk_fma_f32 v[76:77], v[76:77], v[90:91], v[86:87] neg_lo:[0,0,1] neg_hi:[0,0,1]
	v_pk_add_f32 v[86:87], v[94:95], v[106:107] neg_lo:[0,1] neg_hi:[0,1]
	v_pk_fma_f32 v[68:69], v[68:69], v[90:91], v[102:103]
	v_pk_add_f32 v[70:71], v[92:93], v[108:109]
	s_waitcnt vmcnt(0)
	v_mul_f32_e32 v98, v74, v230
	s_waitcnt vmcnt(0)
	v_mul_f32_e32 v100, v66, v234
	v_mul_f32_e32 v102, v74, v234
	v_mul_f32_e32 v230, v66, v230
	v_mov_b32_e32 v66, v75
	v_mov_b32_e32 v234, v231
	v_pk_mul_f32 v[106:107], v[66:67], v[234:235]
	v_mov_b32_e32 v74, v67
	v_pk_mul_f32 v[78:79], v[72:73], v[232:233]
	v_pk_mul_f32 v[232:233], v[64:65], v[232:233]
	v_mov_b32_e32 v99, v106
	v_mov_b32_e32 v101, v107
	v_pk_mul_f32 v[66:67], v[74:75], v[234:235]
	v_pk_fma_f32 v[72:73], v[72:73], v[228:229], v[232:233] neg_lo:[0,0,1] neg_hi:[0,0,1]
	v_pk_add_f32 v[232:233], v[98:99], v[100:101] neg_lo:[0,1] neg_hi:[0,1]
	v_mov_b32_e32 v231, v66
	v_mov_b32_e32 v103, v67
	v_pk_fma_f32 v[64:65], v[64:65], v[228:229], v[78:79]
	v_pk_add_f32 v[66:67], v[230:231], v[102:103]
	v_mov_b32_e32 v74, v232
	v_mov_b32_e32 v75, v233
	v_mov_b32_e32 v78, v86
	v_mov_b32_e32 v79, v87
.LBB0_409:
	s_or_b64 exec, exec, s[0:1]
	v_add_f32_e32 v80, 0, v80
	v_add_f32_e32 v80, v80, v81
	v_add_f32_e32 v80, v80, v82
	v_add_f32_e32 v80, v80, v83
	v_add_f32_e32 v80, v80, v84
	v_add_f32_e32 v80, v80, v85
	v_fmamk_f32 v80, v80, 0x3b2aaaab, v252
	v_mul_f32_e32 v81, 0x4b800000, v80
	v_cmp_gt_f32_e64 s[0:1], s25, v80
	v_mov_b32_e32 v105, v177
	s_nop 0
	v_cndmask_b32_e64 v80, v80, v81, s[0:1]
	v_rsq_f32_e32 v82, v80
	v_mov_b64_e32 v[80:81], s[22:23]
	v_mul_f32_e32 v83, 0x45800000, v82
	v_cndmask_b32_e64 v82, v82, v83, s[0:1]
	v_mul_f32_e32 v82, 0x3dd53b94, v82
	v_pk_mul_f32 v[78:79], v[82:83], v[78:79] op_sel_hi:[0,1]
	v_pk_mul_f32 v[76:77], v[82:83], v[76:77] op_sel_hi:[0,1]
	v_pk_mul_f32 v[74:75], v[82:83], v[74:75] op_sel_hi:[0,1]
	v_pk_mul_f32 v[72:73], v[82:83], v[72:73] op_sel_hi:[0,1]
	s_nop 0
	s_nop 0
	s_nop 0
	s_nop 0
	s_nop 0
	s_nop 0
	s_nop 0
	s_nop 0
	v_mad_i64_i32 v[80:81], s[0:1], v88, s8, v[80:81]
	v_lshl_add_u64 v[80:81], v[80:81], 0, v[128:129]
	s_waitcnt lgkmcnt(0)
	s_nop 0
	v_mov_b32_e32 v83, v72
	s_nop 1
	v_permlane16_swap_b32_e32 v76, v83
	s_waitcnt lgkmcnt(0)
	s_nop 0
	v_mov_b32_e32 v72, v77
	v_mov_b32_e32 v77, v73
	s_nop 1
	v_permlane16_swap_b32_e32 v72, v77
	s_waitcnt lgkmcnt(0)
	s_nop 0
	v_mov_b32_e32 v73, v78
	v_mov_b32_e32 v78, v74
	s_nop 1
	v_permlane16_swap_b32_e32 v73, v78
	s_waitcnt lgkmcnt(0)
	s_nop 0
	v_mov_b32_e32 v74, v79
	s_nop 1
	v_permlane16_swap_b32_e32 v74, v75
	v_cvt_pk_bf16_f32 v72, v76, v72
	v_cvt_pk_bf16_f32 v73, v73, v74
	v_cvt_pk_bf16_f32 v74, v83, v77
	v_lshl_add_u64 v[76:77], v[80:81], 0, v[104:105]
	v_cvt_pk_bf16_f32 v75, v78, v75
	v_lshl_add_u64 v[76:77], v[76:77], 0, v[176:177]
	v_pk_mul_f32 v[70:71], v[82:83], v[70:71] op_sel_hi:[0,1]
	v_pk_mul_f32 v[68:69], v[82:83], v[68:69] op_sel_hi:[0,1]
	v_pk_mul_f32 v[66:67], v[82:83], v[66:67] op_sel_hi:[0,1]
	v_pk_mul_f32 v[64:65], v[82:83], v[64:65] op_sel_hi:[0,1]
	global_store_dwordx4 v[76:77], v[72:75], off
	s_nop 0
	v_cndmask_b32_e32 v77, v71, v67, vcc
	s_nop 0
	s_nop 0
	s_nop 0
	s_nop 0
	s_nop 0
	ds_bpermute_b32 v77, v130, v77
	v_mov_b64_e32 v[72:73], s[34:35]
	v_mad_i64_i32 v[72:73], s[0:1], v88, s8, v[72:73]
	v_lshl_add_u64 v[72:73], v[72:73], 0, v[128:129]
	s_waitcnt lgkmcnt(1)
	s_nop 0
	v_mov_b32_e32 v74, v64
	s_nop 1
	v_permlane16_swap_b32_e32 v68, v74
	s_waitcnt lgkmcnt(1)
	s_nop 0
	v_mov_b32_e32 v64, v69
	v_mov_b32_e32 v69, v65
	s_nop 1
	v_permlane16_swap_b32_e32 v64, v69
	s_waitcnt lgkmcnt(1)
	s_nop 0
	v_mov_b32_e32 v65, v70
	v_mov_b32_e32 v70, v66
	s_nop 1
	v_permlane16_swap_b32_e32 v65, v70
	s_waitcnt lgkmcnt(0)
	v_cndmask_b32_e32 v66, v77, v71, vcc
	v_cvt_pk_bf16_f32 v64, v68, v64
	v_cvt_pk_bf16_f32 v65, v65, v66
	v_cvt_pk_bf16_f32 v66, v74, v69
	v_lshl_add_u64 v[68:69], v[72:73], 0, v[104:105]
	v_cndmask_b32_e32 v67, v67, v77, vcc
	v_lshl_add_u64 v[68:69], v[68:69], 0, v[176:177]
	s_mov_b32 s0, 0x3900000
	v_cvt_pk_bf16_f32 v67, v70, v67
	v_add_co_u32_e64 v68, s[0:1], s0, v68
	v_or_b32_e32 v70, 64, v143
	s_nop 0
	v_addc_co_u32_e64 v69, s[0:1], 0, v69, s[0:1]
	v_or_b32_e32 v72, v144, v70
	global_store_dwordx4 v[68:69], v[64:67], off offset:64
	s_nop 1
	v_mov_b64_e32 v[68:69], v[208:209]
	v_mov_b64_e32 v[64:65], v[204:205]
	v_mov_b64_e32 v[66:67], v[206:207]
	s_and_saveexec_b64 s[0:1], s[40:41]
	s_cbranch_execz .LBB0_411
	v_or_b32_e32 v70, v142, v70
	v_lshlrev_b32_e32 v70, 7, v70
	v_mov_b32_e32 v71, v177
	v_lshl_add_u64 v[82:83], v[134:135], 0, v[70:71]
	v_lshl_add_u64 v[84:85], v[132:133], 0, v[70:71]
	global_load_dwordx4 v[74:77], v[82:83], off
	global_load_dwordx4 v[78:81], v[84:85], off
	global_load_dwordx4 v[228:231], v[82:83], off offset:64
	global_load_dwordx4 v[232:235], v[84:85], off offset:64
	s_waitcnt vmcnt(2)
	v_pk_mul_f32 v[86:87], v[60:61], v[78:79]
	v_pk_mul_f32 v[70:71], v[52:53], v[78:79]
	v_mul_f32_e32 v78, v62, v76
	v_mul_f32_e32 v88, v54, v80
	v_mul_f32_e32 v90, v62, v80
	v_mul_f32_e32 v76, v54, v76
	v_mov_b32_e32 v54, v63
	v_mov_b32_e32 v80, v77
	v_mov_b32_e32 v62, v55
	v_pk_mul_f32 v[92:93], v[54:55], v[80:81]
	v_pk_mul_f32 v[54:55], v[62:63], v[80:81]
	v_mov_b32_e32 v79, v92
	v_mov_b32_e32 v89, v93
	v_mov_b32_e32 v77, v54
	v_mov_b32_e32 v91, v55
	v_pk_fma_f32 v[60:61], v[60:61], v[74:75], v[70:71] neg_lo:[0,0,1] neg_hi:[0,0,1]
	v_pk_add_f32 v[70:71], v[78:79], v[88:89] neg_lo:[0,1] neg_hi:[0,1]
	v_pk_fma_f32 v[52:53], v[52:53], v[74:75], v[86:87]
	v_pk_add_f32 v[54:55], v[76:77], v[90:91]
	s_waitcnt vmcnt(0)
	v_mul_f32_e32 v82, v58, v230
	s_waitcnt vmcnt(0)
	v_mul_f32_e32 v84, v50, v234
	v_mul_f32_e32 v86, v58, v234
	v_mul_f32_e32 v230, v50, v230
	v_mov_b32_e32 v50, v59
	v_mov_b32_e32 v234, v231
	v_pk_mul_f32 v[88:89], v[50:51], v[234:235]
	v_mov_b32_e32 v58, v51
	v_pk_mul_f32 v[62:63], v[56:57], v[232:233]
	v_pk_mul_f32 v[232:233], v[48:49], v[232:233]
	v_mov_b32_e32 v83, v88
	v_mov_b32_e32 v85, v89
	v_pk_mul_f32 v[50:51], v[58:59], v[234:235]
	v_pk_fma_f32 v[56:57], v[56:57], v[228:229], v[232:233] neg_lo:[0,0,1] neg_hi:[0,0,1]
	v_pk_add_f32 v[232:233], v[82:83], v[84:85] neg_lo:[0,1] neg_hi:[0,1]
	v_mov_b32_e32 v231, v50
	v_mov_b32_e32 v87, v51
	v_pk_fma_f32 v[48:49], v[48:49], v[228:229], v[62:63]
	v_pk_add_f32 v[50:51], v[230:231], v[86:87]
	v_mov_b32_e32 v58, v232
	v_mov_b32_e32 v59, v233
	v_mov_b32_e32 v62, v70
	v_mov_b32_e32 v63, v71
.LBB0_411:
	s_or_b64 exec, exec, s[0:1]
	v_add_f32_e32 v64, 0, v64
	v_add_f32_e32 v64, v64, v65
	v_add_f32_e32 v64, v64, v66
	v_add_f32_e32 v64, v64, v67
	v_add_f32_e32 v64, v64, v68
	v_add_f32_e32 v64, v64, v69
	v_fmamk_f32 v64, v64, 0x3b2aaaab, v252
	v_mul_f32_e32 v65, 0x4b800000, v64
	v_cmp_gt_f32_e64 s[0:1], s25, v64
	s_nop 1
	v_cndmask_b32_e64 v64, v64, v65, s[0:1]
	v_rsq_f32_e32 v66, v64
	v_mov_b64_e32 v[64:65], s[22:23]
	v_mul_f32_e32 v67, 0x45800000, v66
	v_cndmask_b32_e64 v66, v66, v67, s[0:1]
	v_mul_f32_e32 v66, 0x3dd53b94, v66
	v_pk_mul_f32 v[62:63], v[66:67], v[62:63] op_sel_hi:[0,1]
	v_pk_mul_f32 v[60:61], v[66:67], v[60:61] op_sel_hi:[0,1]
	v_pk_mul_f32 v[58:59], v[66:67], v[58:59] op_sel_hi:[0,1]
	v_pk_mul_f32 v[56:57], v[66:67], v[56:57] op_sel_hi:[0,1]
	s_nop 0
	s_nop 0
	s_nop 0
	s_nop 0
	s_nop 0
	s_nop 0
	s_nop 0
	s_nop 0
	v_mad_i64_i32 v[64:65], s[0:1], v72, s8, v[64:65]
	v_lshl_add_u64 v[64:65], v[64:65], 0, v[128:129]
	s_waitcnt lgkmcnt(0)
	s_nop 0
	v_mov_b32_e32 v67, v56
	s_nop 1
	v_permlane16_swap_b32_e32 v60, v67
	s_waitcnt lgkmcnt(0)
	s_nop 0
	v_mov_b32_e32 v56, v61
	v_mov_b32_e32 v61, v57
	s_nop 1
	v_permlane16_swap_b32_e32 v56, v61
	s_waitcnt lgkmcnt(0)
	s_nop 0
	v_mov_b32_e32 v57, v62
	v_mov_b32_e32 v62, v58
	s_nop 1
	v_permlane16_swap_b32_e32 v57, v62
	s_waitcnt lgkmcnt(0)
	s_nop 0
	v_mov_b32_e32 v58, v63
	s_nop 1
	v_permlane16_swap_b32_e32 v58, v59
	v_cvt_pk_bf16_f32 v56, v60, v56
	v_cvt_pk_bf16_f32 v57, v57, v58
	v_cvt_pk_bf16_f32 v58, v67, v61
	v_lshl_add_u64 v[60:61], v[64:65], 0, v[104:105]
	v_cvt_pk_bf16_f32 v59, v62, v59
	v_lshl_add_u64 v[60:61], v[60:61], 0, v[176:177]
	v_pk_mul_f32 v[54:55], v[66:67], v[54:55] op_sel_hi:[0,1]
	v_pk_mul_f32 v[52:53], v[66:67], v[52:53] op_sel_hi:[0,1]
	v_pk_mul_f32 v[50:51], v[66:67], v[50:51] op_sel_hi:[0,1]
	v_pk_mul_f32 v[48:49], v[66:67], v[48:49] op_sel_hi:[0,1]
	global_store_dwordx4 v[60:61], v[56:59], off
	s_nop 0
	v_cndmask_b32_e32 v61, v55, v51, vcc
	s_nop 0
	s_nop 0
	s_nop 0
	s_nop 0
	s_nop 0
	ds_bpermute_b32 v61, v130, v61
	v_mov_b64_e32 v[56:57], s[34:35]
	v_mad_i64_i32 v[56:57], s[0:1], v72, s8, v[56:57]
	v_lshl_add_u64 v[56:57], v[56:57], 0, v[128:129]
	s_waitcnt lgkmcnt(1)
	s_nop 0
	v_mov_b32_e32 v58, v48
	s_nop 1
	v_permlane16_swap_b32_e32 v52, v58
	s_waitcnt lgkmcnt(1)
	s_nop 0
	v_mov_b32_e32 v48, v53
	v_mov_b32_e32 v53, v49
	s_nop 1
	v_permlane16_swap_b32_e32 v48, v53
	s_waitcnt lgkmcnt(1)
	s_nop 0
	v_mov_b32_e32 v49, v54
	v_mov_b32_e32 v54, v50
	s_nop 1
	v_permlane16_swap_b32_e32 v49, v54
	s_waitcnt lgkmcnt(0)
	v_cndmask_b32_e32 v50, v61, v55, vcc
	v_cvt_pk_bf16_f32 v48, v52, v48
	v_cvt_pk_bf16_f32 v49, v49, v50
	v_cvt_pk_bf16_f32 v50, v58, v53
	v_lshl_add_u64 v[52:53], v[56:57], 0, v[104:105]
	v_cndmask_b32_e32 v51, v51, v61, vcc
	v_lshl_add_u64 v[52:53], v[52:53], 0, v[176:177]
	s_mov_b32 s0, 0x3900000
	v_cvt_pk_bf16_f32 v51, v54, v51
	v_add_co_u32_e64 v52, s[0:1], s0, v52
	v_or_b32_e32 v54, 0x50, v143
	s_nop 0
	v_addc_co_u32_e64 v53, s[0:1], 0, v53, s[0:1]
	v_or_b32_e32 v56, v144, v54
	global_store_dwordx4 v[52:53], v[48:51], off offset:64
	s_nop 1
	v_mov_b64_e32 v[52:53], v[214:215]
	v_mov_b64_e32 v[48:49], v[210:211]
	v_mov_b64_e32 v[50:51], v[212:213]
	s_and_saveexec_b64 s[0:1], s[40:41]
	s_cbranch_execz .LBB0_413
	v_or_b32_e32 v54, v142, v54
	v_lshlrev_b32_e32 v54, 7, v54
	v_mov_b32_e32 v55, v177
	v_lshl_add_u64 v[66:67], v[134:135], 0, v[54:55]
	v_lshl_add_u64 v[68:69], v[132:133], 0, v[54:55]
	global_load_dwordx4 v[58:61], v[66:67], off
	global_load_dwordx4 v[62:65], v[68:69], off
	global_load_dwordx4 v[228:231], v[66:67], off offset:64
	global_load_dwordx4 v[232:235], v[68:69], off offset:64
	s_waitcnt vmcnt(2)
	v_pk_mul_f32 v[70:71], v[44:45], v[62:63]
	v_pk_mul_f32 v[54:55], v[32:33], v[62:63]
	v_mul_f32_e32 v62, v46, v60
	v_mul_f32_e32 v72, v34, v64
	v_mul_f32_e32 v74, v46, v64
	v_mul_f32_e32 v60, v34, v60
	v_mov_b32_e32 v34, v47
	v_mov_b32_e32 v64, v61
	v_mov_b32_e32 v46, v35
	v_pk_mul_f32 v[76:77], v[34:35], v[64:65]
	v_pk_mul_f32 v[34:35], v[46:47], v[64:65]
	v_mov_b32_e32 v63, v76
	v_mov_b32_e32 v73, v77
	v_mov_b32_e32 v61, v34
	v_mov_b32_e32 v75, v35
	v_pk_fma_f32 v[44:45], v[44:45], v[58:59], v[54:55] neg_lo:[0,0,1] neg_hi:[0,0,1]
	v_pk_add_f32 v[54:55], v[62:63], v[72:73] neg_lo:[0,1] neg_hi:[0,1]
	v_pk_fma_f32 v[32:33], v[32:33], v[58:59], v[70:71]
	v_pk_add_f32 v[34:35], v[60:61], v[74:75]
	s_waitcnt vmcnt(0)
	v_mul_f32_e32 v66, v42, v230
	s_waitcnt vmcnt(0)
	v_mul_f32_e32 v68, v38, v234
	v_mul_f32_e32 v70, v42, v234
	v_mul_f32_e32 v230, v38, v230
	v_mov_b32_e32 v38, v43
	v_mov_b32_e32 v234, v231
	v_pk_mul_f32 v[72:73], v[38:39], v[234:235]
	v_mov_b32_e32 v42, v39
	v_pk_mul_f32 v[46:47], v[40:41], v[232:233]
	v_pk_mul_f32 v[232:233], v[36:37], v[232:233]
	v_mov_b32_e32 v67, v72
	v_mov_b32_e32 v69, v73
	v_pk_mul_f32 v[38:39], v[42:43], v[234:235]
	v_pk_fma_f32 v[40:41], v[40:41], v[228:229], v[232:233] neg_lo:[0,0,1] neg_hi:[0,0,1]
	v_pk_add_f32 v[232:233], v[66:67], v[68:69] neg_lo:[0,1] neg_hi:[0,1]
	v_mov_b32_e32 v231, v38
	v_mov_b32_e32 v71, v39
	v_pk_fma_f32 v[36:37], v[36:37], v[228:229], v[46:47]
	v_pk_add_f32 v[38:39], v[230:231], v[70:71]
	v_mov_b32_e32 v42, v232
	v_mov_b32_e32 v43, v233
	v_mov_b32_e32 v46, v54
	v_mov_b32_e32 v47, v55
.LBB0_413:
	s_or_b64 exec, exec, s[0:1]
	v_add_f32_e32 v48, 0, v48
	v_add_f32_e32 v48, v48, v49
	v_add_f32_e32 v48, v48, v50
	v_add_f32_e32 v48, v48, v51
	v_add_f32_e32 v48, v48, v52
	v_add_f32_e32 v48, v48, v53
	v_fmamk_f32 v48, v48, 0x3b2aaaab, v252
	v_mul_f32_e32 v49, 0x4b800000, v48
	v_cmp_gt_f32_e64 s[0:1], s25, v48
	v_mov_b32_e32 v105, v177
	s_nop 0
	v_cndmask_b32_e64 v48, v48, v49, s[0:1]
	v_rsq_f32_e32 v50, v48
	v_mov_b64_e32 v[48:49], s[22:23]
	v_mul_f32_e32 v51, 0x45800000, v50
	v_cndmask_b32_e64 v50, v50, v51, s[0:1]
	v_mul_f32_e32 v50, 0x3dd53b94, v50
	v_pk_mul_f32 v[46:47], v[50:51], v[46:47] op_sel_hi:[0,1]
	v_pk_mul_f32 v[44:45], v[50:51], v[44:45] op_sel_hi:[0,1]
	v_pk_mul_f32 v[42:43], v[50:51], v[42:43] op_sel_hi:[0,1]
	v_pk_mul_f32 v[40:41], v[50:51], v[40:41] op_sel_hi:[0,1]
	s_nop 0
	s_nop 0
	s_nop 0
	s_nop 0
	s_nop 0
	s_nop 0
	s_nop 0
	s_nop 0
	v_mad_i64_i32 v[48:49], s[0:1], v56, s8, v[48:49]
	v_lshl_add_u64 v[48:49], v[48:49], 0, v[128:129]
	s_waitcnt lgkmcnt(0)
	s_nop 0
	v_mov_b32_e32 v51, v40
	s_nop 1
	v_permlane16_swap_b32_e32 v44, v51
	s_waitcnt lgkmcnt(0)
	s_nop 0
	v_mov_b32_e32 v40, v45
	v_mov_b32_e32 v45, v41
	s_nop 1
	v_permlane16_swap_b32_e32 v40, v45
	s_waitcnt lgkmcnt(0)
	s_nop 0
	v_mov_b32_e32 v41, v46
	v_mov_b32_e32 v46, v42
	s_nop 1
	v_permlane16_swap_b32_e32 v41, v46
	s_waitcnt lgkmcnt(0)
	s_nop 0
	v_mov_b32_e32 v42, v47
	s_nop 1
	v_permlane16_swap_b32_e32 v42, v43
	v_cvt_pk_bf16_f32 v40, v44, v40
	v_cvt_pk_bf16_f32 v41, v41, v42
	v_cvt_pk_bf16_f32 v42, v51, v45
	v_lshl_add_u64 v[44:45], v[48:49], 0, v[104:105]
	v_cvt_pk_bf16_f32 v43, v46, v43
	v_lshl_add_u64 v[44:45], v[44:45], 0, v[176:177]
	v_pk_mul_f32 v[34:35], v[50:51], v[34:35] op_sel_hi:[0,1]
	v_pk_mul_f32 v[32:33], v[50:51], v[32:33] op_sel_hi:[0,1]
	v_pk_mul_f32 v[38:39], v[50:51], v[38:39] op_sel_hi:[0,1]
	v_pk_mul_f32 v[36:37], v[50:51], v[36:37] op_sel_hi:[0,1]
	global_store_dwordx4 v[44:45], v[40:43], off
	v_cndmask_b32_e32 v44, v34, v38, vcc
	v_cndmask_b32_e32 v45, v35, v39, vcc
	s_nop 0
	s_nop 0
	s_nop 0
	s_nop 0
	ds_bpermute_b32 v44, v130, v44
	ds_bpermute_b32 v45, v130, v45
	v_mov_b64_e32 v[40:41], s[34:35]
	v_mad_i64_i32 v[40:41], s[0:1], v56, s8, v[40:41]
	v_lshl_add_u64 v[40:41], v[40:41], 0, v[128:129]
	s_waitcnt lgkmcnt(2)
	s_nop 0
	s_nop 1
	v_permlane16_swap_b32_e32 v32, v36
	s_waitcnt lgkmcnt(2)
	s_nop 0
	s_nop 1
	v_permlane16_swap_b32_e32 v33, v37
	s_waitcnt lgkmcnt(1)
	v_cndmask_b32_e32 v34, v44, v34, vcc
	s_waitcnt lgkmcnt(0)
	v_cndmask_b32_e32 v35, v45, v35, vcc
	v_cvt_pk_bf16_f32 v32, v32, v33
	v_cvt_pk_bf16_f32 v33, v34, v35
	v_cvt_pk_bf16_f32 v34, v36, v37
	v_lshl_add_u64 v[36:37], v[40:41], 0, v[104:105]
	v_cndmask_b32_e32 v38, v38, v44, vcc
	v_cndmask_b32_e32 v39, v39, v45, vcc
	v_lshl_add_u64 v[36:37], v[36:37], 0, v[176:177]
	s_mov_b32 s0, 0x3900000
	v_cvt_pk_bf16_f32 v35, v38, v39
	v_add_co_u32_e64 v36, s[0:1], s0, v36
	v_or_b32_e32 v38, 0x60, v143
	s_nop 0
	v_addc_co_u32_e64 v37, s[0:1], 0, v37, s[0:1]
	v_or_b32_e32 v40, v144, v38
	global_store_dwordx4 v[36:37], v[32:35], off offset:64
	s_nop 1
	v_mov_b64_e32 v[36:37], v[220:221]
	v_mov_b64_e32 v[32:33], v[216:217]
	v_mov_b64_e32 v[34:35], v[218:219]
	s_and_saveexec_b64 s[0:1], s[40:41]
	s_cbranch_execz .LBB0_415
	v_or_b32_e32 v38, v142, v38
	v_lshlrev_b32_e32 v38, 7, v38
	v_mov_b32_e32 v39, v177
	v_lshl_add_u64 v[50:51], v[134:135], 0, v[38:39]
	v_lshl_add_u64 v[52:53], v[132:133], 0, v[38:39]
	global_load_dwordx4 v[42:45], v[50:51], off
	global_load_dwordx4 v[46:49], v[52:53], off
	global_load_dwordx4 v[228:231], v[50:51], off offset:64
	global_load_dwordx4 v[232:235], v[52:53], off offset:64
	s_waitcnt vmcnt(2)
	v_pk_mul_f32 v[54:55], v[24:25], v[46:47]
	v_pk_mul_f32 v[38:39], v[20:21], v[46:47]
	v_mul_f32_e32 v46, v26, v44
	v_mul_f32_e32 v56, v22, v48
	v_mul_f32_e32 v58, v26, v48
	v_mul_f32_e32 v44, v22, v44
	v_mov_b32_e32 v22, v27
	v_mov_b32_e32 v48, v45
	v_mov_b32_e32 v26, v23
	v_pk_mul_f32 v[60:61], v[22:23], v[48:49]
	v_pk_mul_f32 v[22:23], v[26:27], v[48:49]
	v_mov_b32_e32 v47, v60
	v_mov_b32_e32 v57, v61
	v_mov_b32_e32 v45, v22
	v_mov_b32_e32 v59, v23
	v_pk_fma_f32 v[24:25], v[24:25], v[42:43], v[38:39] neg_lo:[0,0,1] neg_hi:[0,0,1]
	v_pk_add_f32 v[38:39], v[46:47], v[56:57] neg_lo:[0,1] neg_hi:[0,1]
	v_pk_fma_f32 v[20:21], v[20:21], v[42:43], v[54:55]
	v_pk_add_f32 v[22:23], v[44:45], v[58:59]
	s_waitcnt vmcnt(0)
	v_mul_f32_e32 v50, v30, v230
	s_waitcnt vmcnt(0)
	v_mul_f32_e32 v52, v18, v234
	v_mul_f32_e32 v54, v30, v234
	v_mul_f32_e32 v230, v18, v230
	v_mov_b32_e32 v18, v31
	v_mov_b32_e32 v234, v231
	v_pk_mul_f32 v[56:57], v[18:19], v[234:235]
	v_mov_b32_e32 v30, v19
	v_pk_mul_f32 v[26:27], v[28:29], v[232:233]
	v_pk_mul_f32 v[232:233], v[16:17], v[232:233]
	v_mov_b32_e32 v51, v56
	v_mov_b32_e32 v53, v57
	v_pk_mul_f32 v[18:19], v[30:31], v[234:235]
	v_pk_fma_f32 v[28:29], v[28:29], v[228:229], v[232:233] neg_lo:[0,0,1] neg_hi:[0,0,1]
	v_pk_add_f32 v[232:233], v[50:51], v[52:53] neg_lo:[0,1] neg_hi:[0,1]
	v_mov_b32_e32 v231, v18
	v_mov_b32_e32 v55, v19
	v_pk_fma_f32 v[16:17], v[16:17], v[228:229], v[26:27]
	v_pk_add_f32 v[18:19], v[230:231], v[54:55]
	v_mov_b32_e32 v30, v232
	v_mov_b32_e32 v31, v233
	v_mov_b32_e32 v26, v38
	v_mov_b32_e32 v27, v39
.LBB0_415:
	s_or_b64 exec, exec, s[0:1]
	v_add_f32_e32 v32, 0, v32
	v_add_f32_e32 v32, v32, v33
	v_add_f32_e32 v32, v32, v34
	v_add_f32_e32 v32, v32, v35
	v_add_f32_e32 v32, v32, v36
	v_add_f32_e32 v32, v32, v37
	v_fmamk_f32 v32, v32, 0x3b2aaaab, v252
	v_mul_f32_e32 v33, 0x4b800000, v32
	v_cmp_gt_f32_e64 s[0:1], s25, v32
	s_nop 1
	v_cndmask_b32_e64 v32, v32, v33, s[0:1]
	v_rsq_f32_e32 v34, v32
	v_mov_b64_e32 v[32:33], s[22:23]
	v_mul_f32_e32 v35, 0x45800000, v34
	v_cndmask_b32_e64 v34, v34, v35, s[0:1]
	v_mul_f32_e32 v34, 0x3dd53b94, v34
	v_pk_mul_f32 v[26:27], v[34:35], v[26:27] op_sel_hi:[0,1]
	v_pk_mul_f32 v[24:25], v[34:35], v[24:25] op_sel_hi:[0,1]
	v_pk_mul_f32 v[30:31], v[34:35], v[30:31] op_sel_hi:[0,1]
	v_pk_mul_f32 v[28:29], v[34:35], v[28:29] op_sel_hi:[0,1]
	v_cndmask_b32_e32 v35, v24, v28, vcc
	s_nop 0
	s_nop 0
	s_nop 0
	ds_bpermute_b32 v35, v130, v35
	s_nop 0
	s_nop 0
	s_nop 0
	v_mad_i64_i32 v[32:33], s[0:1], v40, s8, v[32:33]
	v_lshl_add_u64 v[32:33], v[32:33], 0, v[128:129]
	s_waitcnt lgkmcnt(0)
	v_cndmask_b32_e32 v24, v35, v24, vcc
	v_cndmask_b32_e32 v28, v28, v35, vcc
	s_waitcnt lgkmcnt(0)
	s_nop 0
	s_nop 1
	v_permlane16_swap_b32_e32 v25, v29
	s_waitcnt lgkmcnt(0)
	s_nop 0
	s_waitcnt lgkmcnt(0)
	s_nop 0
	s_nop 1
	v_permlane16_swap_b32_e32 v26, v30
	s_nop 1
	v_permlane16_swap_b32_e32 v27, v31
	v_cvt_pk_bf16_f32 v24, v24, v25
	v_cvt_pk_bf16_f32 v25, v26, v27
	v_cvt_pk_bf16_f32 v26, v28, v29
	v_lshl_add_u64 v[28:29], v[32:33], 0, v[104:105]
	v_cvt_pk_bf16_f32 v27, v30, v31
	v_lshl_add_u64 v[28:29], v[28:29], 0, v[176:177]
	v_pk_mul_f32 v[22:23], v[34:35], v[22:23] op_sel_hi:[0,1]
	v_pk_mul_f32 v[20:21], v[34:35], v[20:21] op_sel_hi:[0,1]
	v_pk_mul_f32 v[18:19], v[34:35], v[18:19] op_sel_hi:[0,1]
	v_pk_mul_f32 v[16:17], v[34:35], v[16:17] op_sel_hi:[0,1]
	global_store_dwordx4 v[28:29], v[24:27], off
	s_nop 0
	v_cndmask_b32_e32 v29, v23, v19, vcc
	s_nop 0
	s_nop 0
	s_nop 0
	s_nop 0
	s_nop 0
	ds_bpermute_b32 v29, v130, v29
	v_mov_b64_e32 v[24:25], s[34:35]
	v_mad_i64_i32 v[24:25], s[0:1], v40, s8, v[24:25]
	v_lshl_add_u64 v[24:25], v[24:25], 0, v[128:129]
	s_waitcnt lgkmcnt(1)
	s_nop 0
	v_mov_b32_e32 v26, v16
	s_nop 1
	v_permlane16_swap_b32_e32 v20, v26
	s_waitcnt lgkmcnt(1)
	s_nop 0
	v_mov_b32_e32 v16, v21
	v_mov_b32_e32 v21, v17
	s_nop 1
	v_permlane16_swap_b32_e32 v16, v21
	s_waitcnt lgkmcnt(1)
	s_nop 0
	v_mov_b32_e32 v17, v22
	v_mov_b32_e32 v22, v18
	s_nop 1
	v_permlane16_swap_b32_e32 v17, v22
	s_waitcnt lgkmcnt(0)
	v_cndmask_b32_e32 v18, v29, v23, vcc
	v_cvt_pk_bf16_f32 v16, v20, v16
	v_cvt_pk_bf16_f32 v17, v17, v18
	v_cvt_pk_bf16_f32 v18, v26, v21
	v_lshl_add_u64 v[20:21], v[24:25], 0, v[104:105]
	v_cndmask_b32_e32 v19, v19, v29, vcc
	v_lshl_add_u64 v[20:21], v[20:21], 0, v[176:177]
	s_mov_b32 s0, 0x3900000
	v_cvt_pk_bf16_f32 v19, v22, v19
	v_add_co_u32_e64 v20, s[0:1], s0, v20
	v_or_b32_e32 v22, 0x70, v143
	s_nop 0
	v_addc_co_u32_e64 v21, s[0:1], 0, v21, s[0:1]
	v_or_b32_e32 v24, v144, v22
	global_store_dwordx4 v[20:21], v[16:19], off offset:64
	s_nop 1
	v_mov_b64_e32 v[20:21], v[226:227]
	v_mov_b64_e32 v[16:17], v[222:223]
	v_mov_b64_e32 v[18:19], v[224:225]
	s_and_saveexec_b64 s[0:1], s[40:41]
	s_cbranch_execz .LBB0_417
	v_or_b32_e32 v22, v142, v22
	v_lshlrev_b32_e32 v22, 7, v22
	v_mov_b32_e32 v23, v177
	v_lshl_add_u64 v[34:35], v[134:135], 0, v[22:23]
	v_lshl_add_u64 v[36:37], v[132:133], 0, v[22:23]
	global_load_dwordx4 v[26:29], v[34:35], off
	global_load_dwordx4 v[30:33], v[36:37], off
	global_load_dwordx4 v[228:231], v[34:35], off offset:64
	global_load_dwordx4 v[232:235], v[36:37], off offset:64
	s_waitcnt vmcnt(2)
	v_pk_mul_f32 v[38:39], v[8:9], v[30:31]
	v_pk_mul_f32 v[22:23], v[0:1], v[30:31]
	v_mul_f32_e32 v30, v10, v28
	v_mul_f32_e32 v40, v2, v32
	v_mul_f32_e32 v42, v10, v32
	v_mul_f32_e32 v28, v2, v28
	v_mov_b32_e32 v2, v11
	v_mov_b32_e32 v32, v29
	v_mov_b32_e32 v10, v3
	v_pk_mul_f32 v[44:45], v[2:3], v[32:33]
	v_pk_mul_f32 v[2:3], v[10:11], v[32:33]
	v_mov_b32_e32 v31, v44
	v_mov_b32_e32 v41, v45
	v_mov_b32_e32 v29, v2
	v_mov_b32_e32 v43, v3
	v_pk_fma_f32 v[8:9], v[8:9], v[26:27], v[22:23] neg_lo:[0,0,1] neg_hi:[0,0,1]
	v_pk_add_f32 v[22:23], v[30:31], v[40:41] neg_lo:[0,1] neg_hi:[0,1]
	v_pk_fma_f32 v[0:1], v[0:1], v[26:27], v[38:39]
	v_pk_add_f32 v[2:3], v[28:29], v[42:43]
	s_waitcnt vmcnt(0)
	v_mul_f32_e32 v34, v14, v230
	s_waitcnt vmcnt(0)
	v_mul_f32_e32 v36, v6, v234
	v_mul_f32_e32 v38, v14, v234
	v_mul_f32_e32 v230, v6, v230
	v_mov_b32_e32 v6, v15
	v_mov_b32_e32 v234, v231
	v_pk_mul_f32 v[40:41], v[6:7], v[234:235]
	v_mov_b32_e32 v14, v7
	v_pk_mul_f32 v[10:11], v[12:13], v[232:233]
	v_pk_mul_f32 v[232:233], v[4:5], v[232:233]
	v_mov_b32_e32 v35, v40
	v_mov_b32_e32 v37, v41
	v_pk_mul_f32 v[6:7], v[14:15], v[234:235]
	v_pk_fma_f32 v[12:13], v[12:13], v[228:229], v[232:233] neg_lo:[0,0,1] neg_hi:[0,0,1]
	v_pk_add_f32 v[232:233], v[34:35], v[36:37] neg_lo:[0,1] neg_hi:[0,1]
	v_mov_b32_e32 v231, v6
	v_mov_b32_e32 v39, v7
	v_pk_fma_f32 v[4:5], v[4:5], v[228:229], v[10:11]
	v_pk_add_f32 v[6:7], v[230:231], v[38:39]
	v_mov_b32_e32 v14, v232
	v_mov_b32_e32 v15, v233
	v_mov_b32_e32 v10, v22
	v_mov_b32_e32 v11, v23
.LBB0_417:
	s_or_b64 exec, exec, s[0:1]
	v_add_f32_e32 v16, 0, v16
	v_add_f32_e32 v16, v16, v17
	v_add_f32_e32 v16, v16, v18
	v_add_f32_e32 v16, v16, v19
	v_add_f32_e32 v16, v16, v20
	v_add_f32_e32 v16, v16, v21
	v_fmamk_f32 v16, v16, 0x3b2aaaab, v252
	v_mul_f32_e32 v17, 0x4b800000, v16
	v_cmp_gt_f32_e64 s[0:1], s25, v16
	v_mov_b32_e32 v105, v177
	s_nop 0
	v_cndmask_b32_e64 v16, v16, v17, s[0:1]
	v_rsq_f32_e32 v18, v16
	v_mov_b64_e32 v[16:17], s[22:23]
	v_mul_f32_e32 v19, 0x45800000, v18
	v_cndmask_b32_e64 v18, v18, v19, s[0:1]
	v_mul_f32_e32 v18, 0x3dd53b94, v18
	v_pk_mul_f32 v[10:11], v[18:19], v[10:11] op_sel_hi:[0,1]
	v_pk_mul_f32 v[8:9], v[18:19], v[8:9] op_sel_hi:[0,1]
	v_pk_mul_f32 v[14:15], v[18:19], v[14:15] op_sel_hi:[0,1]
	v_pk_mul_f32 v[12:13], v[18:19], v[12:13] op_sel_hi:[0,1]
	v_cndmask_b32_e32 v19, v8, v12, vcc
	s_nop 0
	s_nop 0
	s_nop 0
	ds_bpermute_b32 v19, v130, v19
	s_nop 0
	s_nop 0
	s_nop 0
	v_mad_i64_i32 v[16:17], s[0:1], v24, s8, v[16:17]
	v_lshl_add_u64 v[16:17], v[16:17], 0, v[128:129]
	s_waitcnt lgkmcnt(0)
	v_cndmask_b32_e32 v8, v19, v8, vcc
	v_cndmask_b32_e32 v12, v12, v19, vcc
	s_waitcnt lgkmcnt(0)
	s_nop 0
	s_nop 1
	v_permlane16_swap_b32_e32 v9, v13
	s_waitcnt lgkmcnt(0)
	s_nop 0
	s_waitcnt lgkmcnt(0)
	s_nop 0
	s_nop 1
	v_permlane16_swap_b32_e32 v10, v14
	s_nop 1
	v_permlane16_swap_b32_e32 v11, v15
	v_cvt_pk_bf16_f32 v8, v8, v9
	v_cvt_pk_bf16_f32 v9, v10, v11
	v_cvt_pk_bf16_f32 v10, v12, v13
	v_lshl_add_u64 v[12:13], v[16:17], 0, v[104:105]
	v_cvt_pk_bf16_f32 v11, v14, v15
	v_lshl_add_u64 v[12:13], v[12:13], 0, v[176:177]
	v_pk_mul_f32 v[2:3], v[18:19], v[2:3] op_sel_hi:[0,1]
	v_pk_mul_f32 v[0:1], v[18:19], v[0:1] op_sel_hi:[0,1]
	v_pk_mul_f32 v[6:7], v[18:19], v[6:7] op_sel_hi:[0,1]
	v_pk_mul_f32 v[4:5], v[18:19], v[4:5] op_sel_hi:[0,1]
	global_store_dwordx4 v[12:13], v[8:11], off
	v_cndmask_b32_e32 v12, v2, v6, vcc
	v_cndmask_b32_e32 v13, v3, v7, vcc
	s_nop 0
	s_nop 0
	s_nop 0
	s_nop 0
	ds_bpermute_b32 v12, v130, v12
	ds_bpermute_b32 v13, v130, v13
	v_mov_b64_e32 v[8:9], s[34:35]
	v_mad_i64_i32 v[8:9], s[0:1], v24, s8, v[8:9]
	v_lshl_add_u64 v[8:9], v[8:9], 0, v[128:129]
	s_waitcnt lgkmcnt(2)
	s_nop 0
	s_nop 1
	v_permlane16_swap_b32_e32 v0, v4
	s_waitcnt lgkmcnt(2)
	s_nop 0
	s_nop 1
	v_permlane16_swap_b32_e32 v1, v5
	s_waitcnt lgkmcnt(1)
	v_cndmask_b32_e32 v2, v12, v2, vcc
	s_waitcnt lgkmcnt(0)
	v_cndmask_b32_e32 v3, v13, v3, vcc
	v_cvt_pk_bf16_f32 v0, v0, v1
	v_cvt_pk_bf16_f32 v1, v2, v3
	v_cvt_pk_bf16_f32 v2, v4, v5
	v_lshl_add_u64 v[4:5], v[8:9], 0, v[104:105]
	v_lshl_add_u64 v[4:5], v[4:5], 0, v[176:177]
	v_cndmask_b32_e32 v6, v6, v12, vcc
	v_cndmask_b32_e32 v7, v7, v13, vcc
	v_add_co_u32_e32 v4, vcc, 0x3900000, v4
	v_cvt_pk_bf16_f32 v3, v6, v7
	s_nop 0
	v_addc_co_u32_e32 v5, vcc, 0, v5, vcc
	global_store_dwordx4 v[4:5], v[0:3], off offset:64
